# K-loops: LDS-DMA in saddr form (SGPR base + 32-bit VGPR offset), dropping the sixteen 64-bit VALU address adds and the m0 save/restore per iteration (fewer VALU per MFMA)
# speedup vs baseline: 1.0003x; 1.0003x over previous
; #define PG8_STAGE(bufoff, gbase, voff) do { _Pragma("unroll") for (int _i = 0; _i < 2; ++_i) \
;         glds16_asm((const char*)(gbase) + (voff)[_i], ldsb + (unsigned)((bufoff) + _i * 8192)); } while (0)
; #define PG8_LDA(dst, b, h) do { _Pragma("unroll") for (int m = 0; m < 4; ++m) _Pragma("unroll") for (int k = 0; k < 2; ++k) dst[m][k] = *(const PG8_LAS bf16x8*)(lds + PG8_SA(b, h) + aoff + m * 2048 + k * 1024); } while (0)
; #define PG8_LDB(dst, b, h) do { _Pragma("unroll") for (int n = 0; n < 2; ++n) _Pragma("unroll") for (int k = 0; k < 2; ++k) dst[n][k] = *(const PG8_LAS bf16x8*)(lds + PG8_SB(b, h) + boff + n * 2048 + k * 1024); } while (0)
; #define PG8_MMA(ai, bj, At, Bt) do { __builtin_amdgcn_s_setprio(1); _Pragma("unroll") for (int m = 0; m < 4; ++m) _Pragma("unroll") for (int n = 0; n < 2; ++n) _Pragma("unroll") for (int k = 0; k < 2; ++k) \
;         acc[ai][bj][m][n] = __builtin_amdgcn_mfma_f32_16x16x32_bf16(Bt[n][k], At[m][k], acc[ai][bj][m][n], 0, 0, 0); __builtin_amdgcn_s_setprio(0); } while (0)
; #define PG8_WAIT_V(n) asm volatile("s_waitcnt vmcnt(" #n ")" ::: "memory")
; #define PG8_WAIT_L(n) asm volatile("s_waitcnt lgkmcnt(" #n ")" ::: "memory")
; #define PG8_BAR __builtin_amdgcn_s_barrier()
; #define PG8_SCHED __builtin_amdgcn_sched_barrier(0)
; template <class Epi, class Sched, bool ALIGN_EPI = false, bool SP2 = false>
; __device__ __forceinline__ void gemm_phase(PG8_LAS unsigned char* lds, const Gemm g, const Sched& S, const Epi& E, int wave_u) {
;     ...
;             PG8_LDB(B0, 0, 0); PG8_LDB(B1, 0, 1); PG8_SCHED; PG8_LDA(At, 0, 0); PG8_STAGE(PG8_SA(1, 1), a1 + hstep, voffA);
;             PG8_WAIT_V(8); PG8_WAIT_L(0); PG8_BAR; PG8_MMA(0, 0, At, B0); PG8_MMA(0, 1, At, B1); PG8_BAR; PG8_SCHED;
;             PG8_LDA(At, 0, 1); PG8_STAGE(PG8_SB(0, 0), b2, voffB); PG8_STAGE(PG8_SB(0, 1), b2 + hstep, voffB); PG8_STAGE(PG8_SA(0, 0), a2, voffA);
;             PG8_WAIT_V(8); PG8_WAIT_L(0); PG8_BAR; PG8_MMA(1, 0, At, B0); PG8_MMA(1, 1, At, B1); PG8_BAR; PG8_SCHED;
.LBB0_143:
	v_add_u32_e32 v0, 0x10000, v203
	s_waitcnt lgkmcnt(0)
	ds_read_b128 v[134:137], v0
	ds_read_b128 v[138:141], v0 offset:1024
	ds_read_b128 v[142:145], v0 offset:2048
	ds_read_b128 v[146:149], v0 offset:3072
	v_add_u32_e32 v0, 0x14000, v203
	s_add_u32 s1, s88, 0xfffc0080
	ds_read_b128 v[150:153], v0
	ds_read_b128 v[154:157], v0 offset:1024
	ds_read_b128 v[158:161], v0 offset:2048
	ds_read_b128 v[162:165], v0 offset:3072
	s_addc_u32 s46, s89, -1
	s_and_b64 s[44:45], s[44:45], exec
	s_cselect_b32 s56, s90, s1
	s_cselect_b32 s57, s53, s46
	s_cselect_b32 s45, s25, s65
	s_cselect_b32 s44, s91, s64
	s_add_u32 s46, s56, 0x80
	s_addc_u32 s47, s57, 0
	s_add_u32 s48, s44, 0x80
	s_addc_u32 s49, s45, 0
	ds_read_b128 v[166:169], v204
	ds_read_b128 v[182:185], v204 offset:1024
	ds_read_b128 v[186:189], v204 offset:2048
	ds_read_b128 v[206:209], v204 offset:3072
	ds_read_b128 v[210:213], v204 offset:4096
	ds_read_b128 v[224:227], v204 offset:5120
	ds_read_b128 v[228:231], v204 offset:6144
	ds_read_b128 v[232:235], v204 offset:7168
	s_mov_b32 m0, s78
	s_nop 0
	global_load_lds_dwordx4 v170, s[88:89]
	s_mov_b32 m0, s79
	s_nop 0
	global_load_lds_dwordx4 v174, s[88:89]
	s_waitcnt vmcnt(8)
	s_waitcnt lgkmcnt(0)
	s_barrier
	s_setprio 1
	s_waitcnt lgkmcnt(7)
	v_mfma_f32_16x16x32_bf16 v[122:125], v[134:137], v[166:169], v[122:125]
	v_mfma_f32_16x16x32_bf16 v[114:117], v[142:145], v[166:169], v[114:117]
	s_waitcnt lgkmcnt(5)
	v_mfma_f32_16x16x32_bf16 v[102:105], v[134:137], v[186:189], v[102:105]
	v_mfma_f32_16x16x32_bf16 v[98:101], v[142:145], v[186:189], v[98:101]
	s_waitcnt lgkmcnt(3)
	v_mfma_f32_16x16x32_bf16 v[86:89], v[134:137], v[210:213], v[86:89]
	v_mfma_f32_16x16x32_bf16 v[82:85], v[142:145], v[210:213], v[82:85]
	s_waitcnt lgkmcnt(1)
	v_mfma_f32_16x16x32_bf16 v[70:73], v[134:137], v[228:231], v[70:73]
	v_mfma_f32_16x16x32_bf16 v[66:69], v[142:145], v[228:231], v[66:69]
	v_mfma_f32_16x16x32_bf16 v[122:125], v[138:141], v[182:185], v[122:125]
	v_mfma_f32_16x16x32_bf16 v[114:117], v[146:149], v[182:185], v[114:117]
	v_mfma_f32_16x16x32_bf16 v[102:105], v[138:141], v[206:209], v[102:105]
	v_mfma_f32_16x16x32_bf16 v[98:101], v[146:149], v[206:209], v[98:101]
	v_mfma_f32_16x16x32_bf16 v[86:89], v[138:141], v[224:227], v[86:89]
	v_mfma_f32_16x16x32_bf16 v[82:85], v[146:149], v[224:227], v[82:85]
	s_waitcnt lgkmcnt(0)
	v_mfma_f32_16x16x32_bf16 v[70:73], v[138:141], v[232:235], v[70:73]
	v_mfma_f32_16x16x32_bf16 v[66:69], v[146:149], v[232:235], v[66:69]
	s_setprio 0
	s_setprio 1
	v_mfma_f32_16x16x32_bf16 v[126:129], v[150:153], v[166:169], v[126:129]
	v_mfma_f32_16x16x32_bf16 v[118:121], v[158:161], v[166:169], v[118:121]
	v_mfma_f32_16x16x32_bf16 v[110:113], v[150:153], v[186:189], v[110:113]
	v_mfma_f32_16x16x32_bf16 v[106:109], v[158:161], v[186:189], v[106:109]
	v_mfma_f32_16x16x32_bf16 v[94:97], v[150:153], v[210:213], v[94:97]
	v_mfma_f32_16x16x32_bf16 v[90:93], v[158:161], v[210:213], v[90:93]
	v_mfma_f32_16x16x32_bf16 v[78:81], v[150:153], v[228:231], v[78:81]
	v_mfma_f32_16x16x32_bf16 v[74:77], v[158:161], v[228:231], v[74:77]
	v_mfma_f32_16x16x32_bf16 v[126:129], v[154:157], v[182:185], v[126:129]
	v_mfma_f32_16x16x32_bf16 v[118:121], v[162:165], v[182:185], v[118:121]
	v_mfma_f32_16x16x32_bf16 v[110:113], v[154:157], v[206:209], v[110:113]
	v_mfma_f32_16x16x32_bf16 v[106:109], v[162:165], v[206:209], v[106:109]
	v_mfma_f32_16x16x32_bf16 v[94:97], v[154:157], v[224:227], v[94:97]
	v_mfma_f32_16x16x32_bf16 v[90:93], v[162:165], v[224:227], v[90:93]
	v_mfma_f32_16x16x32_bf16 v[78:81], v[154:157], v[232:235], v[78:81]
	v_mfma_f32_16x16x32_bf16 v[74:77], v[162:165], v[232:235], v[74:77]
	s_setprio 0
	s_barrier
	ds_read_b128 v[166:169], v204 offset:16384
	ds_read_b128 v[182:185], v204 offset:17408
	ds_read_b128 v[186:189], v204 offset:18432
	ds_read_b128 v[206:209], v204 offset:19456
	ds_read_b128 v[210:213], v204 offset:20480
	ds_read_b128 v[224:227], v204 offset:21504
	ds_read_b128 v[228:231], v204 offset:22528
	ds_read_b128 v[232:235], v204 offset:23552
	s_mov_b32 m0, s20
	s_nop 0
	global_load_lds_dwordx4 v172, s[44:45]
	s_add_u32 vcc_lo, s44, 0x40000
	s_mov_b32 m0, s21
	s_nop 0
	global_load_lds_dwordx4 v176, s[44:45]
	s_addc_u32 vcc_hi, s45, 0
	s_mov_b32 m0, s35
	s_nop 0
	global_load_lds_dwordx4 v172, vcc
	s_mov_b32 m0, s40
	s_nop 0
	global_load_lds_dwordx4 v176, vcc
	s_mov_b32 m0, s2
	s_nop 0
	global_load_lds_dwordx4 v170, s[56:57]
	s_mov_b32 m0, s41
	s_nop 0
	global_load_lds_dwordx4 v174, s[56:57]
	s_waitcnt vmcnt(8)
	s_waitcnt lgkmcnt(0)
	s_barrier
; #define PG8_STAGE(bufoff, gbase, voff) do { _Pragma("unroll") for (int _i = 0; _i < 2; ++_i) \
;         glds16_asm((const char*)(gbase) + (voff)[_i], ldsb + (unsigned)((bufoff) + _i * 8192)); } while (0)
; #define PG8_LDA(dst, b, h) do { _Pragma("unroll") for (int m = 0; m < 4; ++m) _Pragma("unroll") for (int k = 0; k < 2; ++k) dst[m][k] = *(const PG8_LAS bf16x8*)(lds + PG8_SA(b, h) + aoff + m * 2048 + k * 1024); } while (0)
; #define PG8_LDB(dst, b, h) do { _Pragma("unroll") for (int n = 0; n < 2; ++n) _Pragma("unroll") for (int k = 0; k < 2; ++k) dst[n][k] = *(const PG8_LAS bf16x8*)(lds + PG8_SB(b, h) + boff + n * 2048 + k * 1024); } while (0)
; #define PG8_MMA(ai, bj, At, Bt) do { __builtin_amdgcn_s_setprio(1); _Pragma("unroll") for (int m = 0; m < 4; ++m) _Pragma("unroll") for (int n = 0; n < 2; ++n) _Pragma("unroll") for (int k = 0; k < 2; ++k) \
;         acc[ai][bj][m][n] = __builtin_amdgcn_mfma_f32_16x16x32_bf16(Bt[n][k], At[m][k], acc[ai][bj][m][n], 0, 0, 0); __builtin_amdgcn_s_setprio(0); } while (0)
; #define PG8_WAIT_V(n) asm volatile("s_waitcnt vmcnt(" #n ")" ::: "memory")
; #define PG8_WAIT_L(n) asm volatile("s_waitcnt lgkmcnt(" #n ")" ::: "memory")
; #define PG8_BAR __builtin_amdgcn_s_barrier()
; #define PG8_SCHED __builtin_amdgcn_sched_barrier(0)
; template <class Epi, class Sched, bool ALIGN_EPI = false, bool SP2 = false>
; __device__ __forceinline__ void gemm_phase(PG8_LAS unsigned char* lds, const Gemm g, const Sched& S, const Epi& E, int wave_u) {
;     ...
;             PG8_WAIT_V(8); PG8_WAIT_L(0); PG8_BAR; PG8_MMA(1, 0, At, B0); PG8_MMA(1, 1, At, B1); PG8_BAR; PG8_SCHED;
;             PG8_LDB(B0, 1, 0); PG8_LDB(B1, 1, 1); PG8_SCHED; PG8_LDA(At, 1, 0); PG8_STAGE(PG8_SA(0, 1), a2 + hstep, voffA);
;             PG8_WAIT_V(8); PG8_WAIT_L(0); PG8_BAR; PG8_MMA(0, 0, At, B0); PG8_MMA(0, 1, At, B1); PG8_BAR; PG8_SCHED;
	s_setprio 1
	s_waitcnt lgkmcnt(7)
	v_mfma_f32_16x16x32_bf16 v[54:57], v[134:137], v[166:169], v[54:57]
	v_mfma_f32_16x16x32_bf16 v[50:53], v[142:145], v[166:169], v[50:53]
	s_waitcnt lgkmcnt(5)
	v_mfma_f32_16x16x32_bf16 v[38:41], v[134:137], v[186:189], v[38:41]
	v_mfma_f32_16x16x32_bf16 v[34:37], v[142:145], v[186:189], v[34:37]
	s_waitcnt lgkmcnt(3)
	v_mfma_f32_16x16x32_bf16 v[22:25], v[134:137], v[210:213], v[22:25]
	v_mfma_f32_16x16x32_bf16 v[18:21], v[142:145], v[210:213], v[18:21]
	s_waitcnt lgkmcnt(1)
	v_mfma_f32_16x16x32_bf16 v[6:9], v[134:137], v[228:231], v[6:9]
	v_mfma_f32_16x16x32_bf16 v[2:5], v[142:145], v[228:231], v[2:5]
	v_mfma_f32_16x16x32_bf16 v[54:57], v[138:141], v[182:185], v[54:57]
	v_mfma_f32_16x16x32_bf16 v[50:53], v[146:149], v[182:185], v[50:53]
	v_mfma_f32_16x16x32_bf16 v[38:41], v[138:141], v[206:209], v[38:41]
	v_mfma_f32_16x16x32_bf16 v[34:37], v[146:149], v[206:209], v[34:37]
	v_mfma_f32_16x16x32_bf16 v[22:25], v[138:141], v[224:227], v[22:25]
	v_mfma_f32_16x16x32_bf16 v[18:21], v[146:149], v[224:227], v[18:21]
	s_waitcnt lgkmcnt(0)
	v_mfma_f32_16x16x32_bf16 v[6:9], v[138:141], v[232:235], v[6:9]
	v_mfma_f32_16x16x32_bf16 v[2:5], v[146:149], v[232:235], v[2:5]
	s_setprio 0
	s_setprio 1
	v_mfma_f32_16x16x32_bf16 v[62:65], v[150:153], v[166:169], v[62:65]
	v_mfma_f32_16x16x32_bf16 v[58:61], v[158:161], v[166:169], v[58:61]
	v_mfma_f32_16x16x32_bf16 v[46:49], v[150:153], v[186:189], v[46:49]
	v_mfma_f32_16x16x32_bf16 v[42:45], v[158:161], v[186:189], v[42:45]
	v_mfma_f32_16x16x32_bf16 v[30:33], v[150:153], v[210:213], v[30:33]
	v_mfma_f32_16x16x32_bf16 v[26:29], v[158:161], v[210:213], v[26:29]
	v_mfma_f32_16x16x32_bf16 v[14:17], v[150:153], v[228:231], v[14:17]
	v_mfma_f32_16x16x32_bf16 v[10:13], v[158:161], v[228:231], v[10:13]
	v_mfma_f32_16x16x32_bf16 v[62:65], v[154:157], v[182:185], v[62:65]
	v_mfma_f32_16x16x32_bf16 v[58:61], v[162:165], v[182:185], v[58:61]
	v_mfma_f32_16x16x32_bf16 v[46:49], v[154:157], v[206:209], v[46:49]
	v_mfma_f32_16x16x32_bf16 v[42:45], v[162:165], v[206:209], v[42:45]
	v_mfma_f32_16x16x32_bf16 v[30:33], v[154:157], v[224:227], v[30:33]
	v_mfma_f32_16x16x32_bf16 v[26:29], v[162:165], v[224:227], v[26:29]
	v_mfma_f32_16x16x32_bf16 v[14:17], v[154:157], v[232:235], v[14:17]
	v_mfma_f32_16x16x32_bf16 v[10:13], v[162:165], v[232:235], v[10:13]
	s_setprio 0
	s_barrier
	v_add_u32_e32 v0, 0x18000, v203
	ds_read_b128 v[134:137], v0
	ds_read_b128 v[138:141], v0 offset:1024
	ds_read_b128 v[142:145], v0 offset:2048
	ds_read_b128 v[146:149], v0 offset:3072
	v_add_u32_e32 v0, 0x1c000, v203
	ds_read_b128 v[150:153], v0
	ds_read_b128 v[154:157], v0 offset:1024
	ds_read_b128 v[158:161], v0 offset:2048
	ds_read_b128 v[162:165], v0 offset:3072
	ds_read_b128 v[166:169], v204 offset:32768
	ds_read_b128 v[182:185], v204 offset:33792
	ds_read_b128 v[186:189], v204 offset:34816
	ds_read_b128 v[206:209], v204 offset:35840
	ds_read_b128 v[210:213], v204 offset:36864
	ds_read_b128 v[224:227], v204 offset:37888
	ds_read_b128 v[228:231], v204 offset:38912
	ds_read_b128 v[232:235], v204 offset:39936
	s_add_u32 s56, s56, 0x40000
	s_addc_u32 s57, s57, 0
	s_mov_b32 m0, s52
	s_nop 0
	global_load_lds_dwordx4 v170, s[56:57]
	s_mov_b32 m0, s58
	s_nop 0
	global_load_lds_dwordx4 v174, s[56:57]
	s_waitcnt vmcnt(8)
	s_waitcnt lgkmcnt(0)
	s_barrier
	s_setprio 1
	s_waitcnt lgkmcnt(7)
	v_mfma_f32_16x16x32_bf16 v[122:125], v[134:137], v[166:169], v[122:125]
	v_mfma_f32_16x16x32_bf16 v[114:117], v[142:145], v[166:169], v[114:117]
	s_waitcnt lgkmcnt(5)
	v_mfma_f32_16x16x32_bf16 v[102:105], v[134:137], v[186:189], v[102:105]
	v_mfma_f32_16x16x32_bf16 v[98:101], v[142:145], v[186:189], v[98:101]
	s_waitcnt lgkmcnt(3)
	v_mfma_f32_16x16x32_bf16 v[86:89], v[134:137], v[210:213], v[86:89]
	v_mfma_f32_16x16x32_bf16 v[82:85], v[142:145], v[210:213], v[82:85]
	s_waitcnt lgkmcnt(1)
	v_mfma_f32_16x16x32_bf16 v[70:73], v[134:137], v[228:231], v[70:73]
	v_mfma_f32_16x16x32_bf16 v[66:69], v[142:145], v[228:231], v[66:69]
	v_mfma_f32_16x16x32_bf16 v[122:125], v[138:141], v[182:185], v[122:125]
	v_mfma_f32_16x16x32_bf16 v[114:117], v[146:149], v[182:185], v[114:117]
	v_mfma_f32_16x16x32_bf16 v[102:105], v[138:141], v[206:209], v[102:105]
	v_mfma_f32_16x16x32_bf16 v[98:101], v[146:149], v[206:209], v[98:101]
	v_mfma_f32_16x16x32_bf16 v[86:89], v[138:141], v[224:227], v[86:89]
	v_mfma_f32_16x16x32_bf16 v[82:85], v[146:149], v[224:227], v[82:85]
	s_waitcnt lgkmcnt(0)
	v_mfma_f32_16x16x32_bf16 v[70:73], v[138:141], v[232:235], v[70:73]
	v_mfma_f32_16x16x32_bf16 v[66:69], v[146:149], v[232:235], v[66:69]
	s_setprio 0
	s_setprio 1
	v_mfma_f32_16x16x32_bf16 v[126:129], v[150:153], v[166:169], v[126:129]
	v_mfma_f32_16x16x32_bf16 v[118:121], v[158:161], v[166:169], v[118:121]
	v_mfma_f32_16x16x32_bf16 v[110:113], v[150:153], v[186:189], v[110:113]
	v_mfma_f32_16x16x32_bf16 v[106:109], v[158:161], v[186:189], v[106:109]
	v_mfma_f32_16x16x32_bf16 v[94:97], v[150:153], v[210:213], v[94:97]
	v_mfma_f32_16x16x32_bf16 v[90:93], v[158:161], v[210:213], v[90:93]
	v_mfma_f32_16x16x32_bf16 v[78:81], v[150:153], v[228:231], v[78:81]
	v_mfma_f32_16x16x32_bf16 v[74:77], v[158:161], v[228:231], v[74:77]
	v_mfma_f32_16x16x32_bf16 v[126:129], v[154:157], v[182:185], v[126:129]
	v_mfma_f32_16x16x32_bf16 v[118:121], v[162:165], v[182:185], v[118:121]
	v_mfma_f32_16x16x32_bf16 v[110:113], v[154:157], v[206:209], v[110:113]
	v_mfma_f32_16x16x32_bf16 v[106:109], v[162:165], v[206:209], v[106:109]
	v_mfma_f32_16x16x32_bf16 v[94:97], v[154:157], v[224:227], v[94:97]
	v_mfma_f32_16x16x32_bf16 v[90:93], v[162:165], v[224:227], v[90:93]
	v_mfma_f32_16x16x32_bf16 v[78:81], v[154:157], v[232:235], v[78:81]
	v_mfma_f32_16x16x32_bf16 v[74:77], v[162:165], v[232:235], v[74:77]
	s_setprio 0
	s_barrier
; #define PG8_STAGE(bufoff, gbase, voff) do { _Pragma("unroll") for (int _i = 0; _i < 2; ++_i) \
;         glds16_asm((const char*)(gbase) + (voff)[_i], ldsb + (unsigned)((bufoff) + _i * 8192)); } while (0)
; #define PG8_LDA(dst, b, h) do { _Pragma("unroll") for (int m = 0; m < 4; ++m) _Pragma("unroll") for (int k = 0; k < 2; ++k) dst[m][k] = *(const PG8_LAS bf16x8*)(lds + PG8_SA(b, h) + aoff + m * 2048 + k * 1024); } while (0)
; #define PG8_MMA(ai, bj, At, Bt) do { __builtin_amdgcn_s_setprio(1); _Pragma("unroll") for (int m = 0; m < 4; ++m) _Pragma("unroll") for (int n = 0; n < 2; ++n) _Pragma("unroll") for (int k = 0; k < 2; ++k) \
;         acc[ai][bj][m][n] = __builtin_amdgcn_mfma_f32_16x16x32_bf16(Bt[n][k], At[m][k], acc[ai][bj][m][n], 0, 0, 0); __builtin_amdgcn_s_setprio(0); } while (0)
; #define PG8_WAIT_V(n) asm volatile("s_waitcnt vmcnt(" #n ")" ::: "memory")
; #define PG8_WAIT_L(n) asm volatile("s_waitcnt lgkmcnt(" #n ")" ::: "memory")
; #define PG8_BAR __builtin_amdgcn_s_barrier()
; #define PG8_SCHED __builtin_amdgcn_sched_barrier(0)
; template <class Epi, class Sched, bool ALIGN_EPI = false, bool SP2 = false>
; __device__ __forceinline__ void gemm_phase(PG8_LAS unsigned char* lds, const Gemm g, const Sched& S, const Epi& E, int wave_u) {
;     ...
;         for (int t = 0; t < nt; t += 2) {
;     ...
;             PG8_LDA(At, 1, 1); PG8_STAGE(PG8_SB(1, 0), b3, voffB); PG8_STAGE(PG8_SB(1, 1), b3 + hstep, voffB); PG8_STAGE(PG8_SA(1, 0), a3, voffA);
;             PG8_WAIT_V(8); PG8_WAIT_L(0); PG8_BAR; PG8_MMA(1, 0, At, B0); PG8_MMA(1, 1, At, B1); PG8_BAR; PG8_SCHED;
	ds_read_b128 v[166:169], v204 offset:49152
	ds_read_b128 v[182:185], v204 offset:50176
	ds_read_b128 v[186:189], v204 offset:51200
	ds_read_b128 v[206:209], v204 offset:52224
	ds_read_b128 v[210:213], v204 offset:53248
	ds_read_b128 v[224:227], v204 offset:54272
	ds_read_b128 v[228:231], v204 offset:55296
	ds_read_b128 v[232:235], v204 offset:56320
	s_mov_b32 m0, s60
	s_nop 0
	global_load_lds_dwordx4 v172, s[48:49]
	s_add_u32 s44, s44, 0x40080
	s_mov_b32 m0, s61
	s_nop 0
	global_load_lds_dwordx4 v176, s[48:49]
	s_addc_u32 s45, s45, 0
	s_mov_b32 m0, s67
	s_nop 0
	global_load_lds_dwordx4 v172, s[44:45]
	s_mov_b32 m0, s75
	s_nop 0
	global_load_lds_dwordx4 v176, s[44:45]
	s_mov_b32 m0, s63
	s_nop 0
	global_load_lds_dwordx4 v170, s[46:47]
	s_mov_b32 m0, s66
	s_nop 0
	global_load_lds_dwordx4 v174, s[46:47]
	s_waitcnt vmcnt(8)
	s_waitcnt lgkmcnt(0)
	s_barrier
	s_setprio 1
	s_waitcnt lgkmcnt(7)
	v_mfma_f32_16x16x32_bf16 v[54:57], v[134:137], v[166:169], v[54:57]
	v_mfma_f32_16x16x32_bf16 v[50:53], v[142:145], v[166:169], v[50:53]
	s_waitcnt lgkmcnt(5)
	v_mfma_f32_16x16x32_bf16 v[38:41], v[134:137], v[186:189], v[38:41]
	v_mfma_f32_16x16x32_bf16 v[34:37], v[142:145], v[186:189], v[34:37]
	s_waitcnt lgkmcnt(3)
	v_mfma_f32_16x16x32_bf16 v[22:25], v[134:137], v[210:213], v[22:25]
	v_mfma_f32_16x16x32_bf16 v[18:21], v[142:145], v[210:213], v[18:21]
	s_waitcnt lgkmcnt(1)
	v_mfma_f32_16x16x32_bf16 v[6:9], v[134:137], v[228:231], v[6:9]
	v_mfma_f32_16x16x32_bf16 v[2:5], v[142:145], v[228:231], v[2:5]
	v_mfma_f32_16x16x32_bf16 v[54:57], v[138:141], v[182:185], v[54:57]
	v_mfma_f32_16x16x32_bf16 v[50:53], v[146:149], v[182:185], v[50:53]
	v_mfma_f32_16x16x32_bf16 v[38:41], v[138:141], v[206:209], v[38:41]
	v_mfma_f32_16x16x32_bf16 v[34:37], v[146:149], v[206:209], v[34:37]
	v_mfma_f32_16x16x32_bf16 v[22:25], v[138:141], v[224:227], v[22:25]
	v_mfma_f32_16x16x32_bf16 v[18:21], v[146:149], v[224:227], v[18:21]
	s_waitcnt lgkmcnt(0)
	v_mfma_f32_16x16x32_bf16 v[6:9], v[138:141], v[232:235], v[6:9]
	v_mfma_f32_16x16x32_bf16 v[2:5], v[146:149], v[232:235], v[2:5]
	s_setprio 0
	s_setprio 1
	v_mfma_f32_16x16x32_bf16 v[62:65], v[150:153], v[166:169], v[62:65]
	v_mfma_f32_16x16x32_bf16 v[58:61], v[158:161], v[166:169], v[58:61]
	v_mfma_f32_16x16x32_bf16 v[46:49], v[150:153], v[186:189], v[46:49]
	v_mfma_f32_16x16x32_bf16 v[42:45], v[158:161], v[186:189], v[42:45]
	v_mfma_f32_16x16x32_bf16 v[30:33], v[150:153], v[210:213], v[30:33]
	v_mfma_f32_16x16x32_bf16 v[26:29], v[158:161], v[210:213], v[26:29]
	v_mfma_f32_16x16x32_bf16 v[14:17], v[150:153], v[228:231], v[14:17]
	v_mfma_f32_16x16x32_bf16 v[10:13], v[158:161], v[228:231], v[10:13]
	v_mfma_f32_16x16x32_bf16 v[62:65], v[154:157], v[182:185], v[62:65]
	v_mfma_f32_16x16x32_bf16 v[58:61], v[162:165], v[182:185], v[58:61]
	v_mfma_f32_16x16x32_bf16 v[46:49], v[154:157], v[206:209], v[46:49]
	v_mfma_f32_16x16x32_bf16 v[42:45], v[162:165], v[206:209], v[42:45]
	v_mfma_f32_16x16x32_bf16 v[30:33], v[154:157], v[224:227], v[30:33]
	v_mfma_f32_16x16x32_bf16 v[26:29], v[162:165], v[224:227], v[26:29]
	v_mfma_f32_16x16x32_bf16 v[14:17], v[154:157], v[232:235], v[14:17]
	v_mfma_f32_16x16x32_bf16 v[10:13], v[162:165], v[232:235], v[10:13]
	s_setprio 0
	s_barrier
	s_add_i32 s84, s84, 2
	s_add_u32 s88, s88, 0x100
	s_addc_u32 s89, s89, 0
	s_add_u32 s64, s64, 0x100
	s_addc_u32 s65, s65, 0
	s_cmp_gt_u32 s84, 13
	s_cbranch_scc1 .LBB0_146

; #define PG8_STAGE(bufoff, gbase, voff) do { _Pragma("unroll") for (int _i = 0; _i < 2; ++_i) \
;         glds16_asm((const char*)(gbase) + (voff)[_i], ldsb + (unsigned)((bufoff) + _i * 8192)); } while (0)
; #define PG8_LDA(dst, b, h) do { _Pragma("unroll") for (int m = 0; m < 4; ++m) _Pragma("unroll") for (int k = 0; k < 2; ++k) dst[m][k] = *(const PG8_LAS bf16x8*)(lds + PG8_SA(b, h) + aoff + m * 2048 + k * 1024); } while (0)
; #define PG8_LDB(dst, b, h) do { _Pragma("unroll") for (int n = 0; n < 2; ++n) _Pragma("unroll") for (int k = 0; k < 2; ++k) dst[n][k] = *(const PG8_LAS bf16x8*)(lds + PG8_SB(b, h) + boff + n * 2048 + k * 1024); } while (0)
; #define PG8_MMA(ai, bj, At, Bt) do { __builtin_amdgcn_s_setprio(1); _Pragma("unroll") for (int m = 0; m < 4; ++m) _Pragma("unroll") for (int n = 0; n < 2; ++n) _Pragma("unroll") for (int k = 0; k < 2; ++k) \
;         acc[ai][bj][m][n] = __builtin_amdgcn_mfma_f32_16x16x32_bf16(Bt[n][k], At[m][k], acc[ai][bj][m][n], 0, 0, 0); __builtin_amdgcn_s_setprio(0); } while (0)
; #define PG8_WAIT_V(n) asm volatile("s_waitcnt vmcnt(" #n ")" ::: "memory")
; #define PG8_WAIT_L(n) asm volatile("s_waitcnt lgkmcnt(" #n ")" ::: "memory")
; #define PG8_BAR __builtin_amdgcn_s_barrier()
; #define PG8_SCHED __builtin_amdgcn_sched_barrier(0)
; template <class Epi, class Sched, bool ALIGN_EPI = false, bool SP2 = false>
; __device__ __forceinline__ void gemm_phase(PG8_LAS unsigned char* lds, const Gemm g, const Sched& S, const Epi& E, int wave_u) {
;     ...
;             PG8_LDB(B0, 0, 0); PG8_LDB(B1, 0, 1); PG8_SCHED; PG8_LDA(At, 0, 0); PG8_STAGE(PG8_SA(1, 1), a1 + hstep, voffA);
;             PG8_WAIT_V(8); PG8_WAIT_L(0); PG8_BAR; PG8_MMA(0, 0, At, B0); PG8_MMA(0, 1, At, B1); PG8_BAR; PG8_SCHED;
;             PG8_LDA(At, 0, 1); PG8_STAGE(PG8_SB(0, 0), b2, voffB); PG8_STAGE(PG8_SB(0, 1), b2 + hstep, voffB); PG8_STAGE(PG8_SA(0, 0), a2, voffA);
;             PG8_WAIT_V(8); PG8_WAIT_L(0); PG8_BAR; PG8_MMA(1, 0, At, B0); PG8_MMA(1, 1, At, B1); PG8_BAR; PG8_SCHED;
.LBB0_264:
	v_add_u32_e32 v0, 0x10000, v211
	s_waitcnt lgkmcnt(0)
	ds_read_b128 v[130:133], v0
	ds_read_b128 v[138:141], v0 offset:1024
	ds_read_b128 v[142:145], v0 offset:2048
	ds_read_b128 v[146:149], v0 offset:3072
	v_add_u32_e32 v0, 0x14000, v211
	s_add_u32 s1, s88, 0xfffc0080
	ds_read_b128 v[150:153], v0
	ds_read_b128 v[154:157], v0 offset:1024
	ds_read_b128 v[158:161], v0 offset:2048
	ds_read_b128 v[162:165], v0 offset:3072
	s_addc_u32 s46, s89, -1
	s_and_b64 s[44:45], s[44:45], exec
	s_cselect_b32 s56, s19, s1
	s_cselect_b32 s57, s13, s46
	s_cselect_b32 s45, s17, s41
	s_cselect_b32 s44, s29, s40
	s_add_u32 s46, s56, 0x80
	s_addc_u32 s47, s57, 0
	s_add_u32 s48, s44, 0x80
	s_addc_u32 s49, s45, 0
	ds_read_b128 v[166:169], v212
	ds_read_b128 v[170:173], v212 offset:1024
	ds_read_b128 v[174:177], v212 offset:2048
	ds_read_b128 v[198:201], v212 offset:3072
	ds_read_b128 v[224:227], v212 offset:4096
	ds_read_b128 v[228:231], v212 offset:5120
	ds_read_b128 v[232:235], v212 offset:6144
	ds_read_b128 v[236:239], v212 offset:7168
	s_mov_b32 m0, s27
	s_nop 0
	global_load_lds_dwordx4 v178, s[88:89]
	s_mov_b32 m0, s60
	s_nop 0
	global_load_lds_dwordx4 v182, s[88:89]
	s_waitcnt vmcnt(8)
	s_waitcnt lgkmcnt(0)
	s_barrier
	s_setprio 1
	s_waitcnt lgkmcnt(7)
	v_mfma_f32_16x16x32_bf16 v[134:137], v[130:133], v[166:169], v[134:137]
	v_mfma_f32_16x16x32_bf16 v[122:125], v[142:145], v[166:169], v[122:125]
	s_waitcnt lgkmcnt(5)
	v_mfma_f32_16x16x32_bf16 v[110:113], v[130:133], v[174:177], v[110:113]
	v_mfma_f32_16x16x32_bf16 v[106:109], v[142:145], v[174:177], v[106:109]
	s_waitcnt lgkmcnt(3)
	v_mfma_f32_16x16x32_bf16 v[94:97], v[130:133], v[224:227], v[94:97]
	v_mfma_f32_16x16x32_bf16 v[90:93], v[142:145], v[224:227], v[90:93]
	s_waitcnt lgkmcnt(1)
	v_mfma_f32_16x16x32_bf16 v[78:81], v[130:133], v[232:235], v[78:81]
	v_mfma_f32_16x16x32_bf16 v[74:77], v[142:145], v[232:235], v[74:77]
	v_mfma_f32_16x16x32_bf16 v[134:137], v[138:141], v[170:173], v[134:137]
	v_mfma_f32_16x16x32_bf16 v[122:125], v[146:149], v[170:173], v[122:125]
	v_mfma_f32_16x16x32_bf16 v[110:113], v[138:141], v[198:201], v[110:113]
	v_mfma_f32_16x16x32_bf16 v[106:109], v[146:149], v[198:201], v[106:109]
	v_mfma_f32_16x16x32_bf16 v[94:97], v[138:141], v[228:231], v[94:97]
	v_mfma_f32_16x16x32_bf16 v[90:93], v[146:149], v[228:231], v[90:93]
	s_waitcnt lgkmcnt(0)
	v_mfma_f32_16x16x32_bf16 v[78:81], v[138:141], v[236:239], v[78:81]
	v_mfma_f32_16x16x32_bf16 v[74:77], v[146:149], v[236:239], v[74:77]
	s_setprio 0
	s_setprio 1
	v_mfma_f32_16x16x32_bf16 v[118:121], v[150:153], v[166:169], v[118:121]
	v_mfma_f32_16x16x32_bf16 v[114:117], v[158:161], v[166:169], v[114:117]
	v_mfma_f32_16x16x32_bf16 v[102:105], v[150:153], v[174:177], v[102:105]
	v_mfma_f32_16x16x32_bf16 v[98:101], v[158:161], v[174:177], v[98:101]
	v_mfma_f32_16x16x32_bf16 v[86:89], v[150:153], v[224:227], v[86:89]
	v_mfma_f32_16x16x32_bf16 v[82:85], v[158:161], v[224:227], v[82:85]
	v_mfma_f32_16x16x32_bf16 v[70:73], v[150:153], v[232:235], v[70:73]
	v_mfma_f32_16x16x32_bf16 v[66:69], v[158:161], v[232:235], v[66:69]
	v_mfma_f32_16x16x32_bf16 v[118:121], v[154:157], v[170:173], v[118:121]
	v_mfma_f32_16x16x32_bf16 v[114:117], v[162:165], v[170:173], v[114:117]
	v_mfma_f32_16x16x32_bf16 v[102:105], v[154:157], v[198:201], v[102:105]
	v_mfma_f32_16x16x32_bf16 v[98:101], v[162:165], v[198:201], v[98:101]
	v_mfma_f32_16x16x32_bf16 v[86:89], v[154:157], v[228:231], v[86:89]
	v_mfma_f32_16x16x32_bf16 v[82:85], v[162:165], v[228:231], v[82:85]
	v_mfma_f32_16x16x32_bf16 v[70:73], v[154:157], v[236:239], v[70:73]
	v_mfma_f32_16x16x32_bf16 v[66:69], v[162:165], v[236:239], v[66:69]
	s_setprio 0
	s_barrier
	ds_read_b128 v[166:169], v212 offset:16384
	ds_read_b128 v[170:173], v212 offset:17408
	ds_read_b128 v[174:177], v212 offset:18432
	ds_read_b128 v[198:201], v212 offset:19456
	ds_read_b128 v[224:227], v212 offset:20480
	ds_read_b128 v[228:231], v212 offset:21504
	ds_read_b128 v[232:235], v212 offset:22528
	ds_read_b128 v[236:239], v212 offset:23552
	s_mov_b32 m0, s63
	s_nop 0
	global_load_lds_dwordx4 v180, s[44:45]
	s_add_u32 s58, s44, 0x40000
	s_mov_b32 m0, s86
	s_nop 0
	global_load_lds_dwordx4 v184, s[44:45]
	s_addc_u32 s59, s45, 0
	s_mov_b32 m0, s87
	s_nop 0
	global_load_lds_dwordx4 v180, s[58:59]
	s_mov_b32 m0, s90
	s_nop 0
	global_load_lds_dwordx4 v184, s[58:59]
	s_mov_b32 m0, s2
	s_nop 0
	global_load_lds_dwordx4 v178, s[56:57]
	s_mov_b32 m0, s91
	s_nop 0
	global_load_lds_dwordx4 v182, s[56:57]
	s_waitcnt vmcnt(8)
	s_waitcnt lgkmcnt(0)
	s_barrier
; #define PG8_STAGE(bufoff, gbase, voff) do { _Pragma("unroll") for (int _i = 0; _i < 2; ++_i) \
;         glds16_asm((const char*)(gbase) + (voff)[_i], ldsb + (unsigned)((bufoff) + _i * 8192)); } while (0)
; #define PG8_LDA(dst, b, h) do { _Pragma("unroll") for (int m = 0; m < 4; ++m) _Pragma("unroll") for (int k = 0; k < 2; ++k) dst[m][k] = *(const PG8_LAS bf16x8*)(lds + PG8_SA(b, h) + aoff + m * 2048 + k * 1024); } while (0)
; #define PG8_LDB(dst, b, h) do { _Pragma("unroll") for (int n = 0; n < 2; ++n) _Pragma("unroll") for (int k = 0; k < 2; ++k) dst[n][k] = *(const PG8_LAS bf16x8*)(lds + PG8_SB(b, h) + boff + n * 2048 + k * 1024); } while (0)
; #define PG8_MMA(ai, bj, At, Bt) do { __builtin_amdgcn_s_setprio(1); _Pragma("unroll") for (int m = 0; m < 4; ++m) _Pragma("unroll") for (int n = 0; n < 2; ++n) _Pragma("unroll") for (int k = 0; k < 2; ++k) \
;         acc[ai][bj][m][n] = __builtin_amdgcn_mfma_f32_16x16x32_bf16(Bt[n][k], At[m][k], acc[ai][bj][m][n], 0, 0, 0); __builtin_amdgcn_s_setprio(0); } while (0)
; #define PG8_WAIT_V(n) asm volatile("s_waitcnt vmcnt(" #n ")" ::: "memory")
; #define PG8_WAIT_L(n) asm volatile("s_waitcnt lgkmcnt(" #n ")" ::: "memory")
; #define PG8_BAR __builtin_amdgcn_s_barrier()
; #define PG8_SCHED __builtin_amdgcn_sched_barrier(0)
; template <class Epi, class Sched, bool ALIGN_EPI = false, bool SP2 = false>
; __device__ __forceinline__ void gemm_phase(PG8_LAS unsigned char* lds, const Gemm g, const Sched& S, const Epi& E, int wave_u) {
;     ...
;             PG8_WAIT_V(8); PG8_WAIT_L(0); PG8_BAR; PG8_MMA(1, 0, At, B0); PG8_MMA(1, 1, At, B1); PG8_BAR; PG8_SCHED;
;             PG8_LDB(B0, 1, 0); PG8_LDB(B1, 1, 1); PG8_SCHED; PG8_LDA(At, 1, 0); PG8_STAGE(PG8_SA(0, 1), a2 + hstep, voffA);
;             PG8_WAIT_V(8); PG8_WAIT_L(0); PG8_BAR; PG8_MMA(0, 0, At, B0); PG8_MMA(0, 1, At, B1); PG8_BAR; PG8_SCHED;
	s_setprio 1
	s_waitcnt lgkmcnt(7)
	v_mfma_f32_16x16x32_bf16 v[62:65], v[130:133], v[166:169], v[62:65]
	v_mfma_f32_16x16x32_bf16 v[58:61], v[142:145], v[166:169], v[58:61]
	s_waitcnt lgkmcnt(5)
	v_mfma_f32_16x16x32_bf16 v[46:49], v[130:133], v[174:177], v[46:49]
	v_mfma_f32_16x16x32_bf16 v[42:45], v[142:145], v[174:177], v[42:45]
	s_waitcnt lgkmcnt(3)
	v_mfma_f32_16x16x32_bf16 v[30:33], v[130:133], v[224:227], v[30:33]
	v_mfma_f32_16x16x32_bf16 v[26:29], v[142:145], v[224:227], v[26:29]
	s_waitcnt lgkmcnt(1)
	v_mfma_f32_16x16x32_bf16 v[14:17], v[130:133], v[232:235], v[14:17]
	v_mfma_f32_16x16x32_bf16 v[10:13], v[142:145], v[232:235], v[10:13]
	v_mfma_f32_16x16x32_bf16 v[62:65], v[138:141], v[170:173], v[62:65]
	v_mfma_f32_16x16x32_bf16 v[58:61], v[146:149], v[170:173], v[58:61]
	v_mfma_f32_16x16x32_bf16 v[46:49], v[138:141], v[198:201], v[46:49]
	v_mfma_f32_16x16x32_bf16 v[42:45], v[146:149], v[198:201], v[42:45]
	v_mfma_f32_16x16x32_bf16 v[30:33], v[138:141], v[228:231], v[30:33]
	v_mfma_f32_16x16x32_bf16 v[26:29], v[146:149], v[228:231], v[26:29]
	s_waitcnt lgkmcnt(0)
	v_mfma_f32_16x16x32_bf16 v[14:17], v[138:141], v[236:239], v[14:17]
	v_mfma_f32_16x16x32_bf16 v[10:13], v[146:149], v[236:239], v[10:13]
	s_setprio 0
	s_setprio 1
	v_mfma_f32_16x16x32_bf16 v[54:57], v[150:153], v[166:169], v[54:57]
	v_mfma_f32_16x16x32_bf16 v[50:53], v[158:161], v[166:169], v[50:53]
	v_mfma_f32_16x16x32_bf16 v[38:41], v[150:153], v[174:177], v[38:41]
	v_mfma_f32_16x16x32_bf16 v[34:37], v[158:161], v[174:177], v[34:37]
	v_mfma_f32_16x16x32_bf16 v[22:25], v[150:153], v[224:227], v[22:25]
	v_mfma_f32_16x16x32_bf16 v[18:21], v[158:161], v[224:227], v[18:21]
	v_mfma_f32_16x16x32_bf16 v[6:9], v[150:153], v[232:235], v[6:9]
	v_mfma_f32_16x16x32_bf16 v[2:5], v[158:161], v[232:235], v[2:5]
	v_mfma_f32_16x16x32_bf16 v[54:57], v[154:157], v[170:173], v[54:57]
	v_mfma_f32_16x16x32_bf16 v[50:53], v[162:165], v[170:173], v[50:53]
	v_mfma_f32_16x16x32_bf16 v[38:41], v[154:157], v[198:201], v[38:41]
	v_mfma_f32_16x16x32_bf16 v[34:37], v[162:165], v[198:201], v[34:37]
	v_mfma_f32_16x16x32_bf16 v[22:25], v[154:157], v[228:231], v[22:25]
	v_mfma_f32_16x16x32_bf16 v[18:21], v[162:165], v[228:231], v[18:21]
	v_mfma_f32_16x16x32_bf16 v[6:9], v[154:157], v[236:239], v[6:9]
	v_mfma_f32_16x16x32_bf16 v[2:5], v[162:165], v[236:239], v[2:5]
	s_setprio 0
	s_barrier
	v_add_u32_e32 v0, 0x18000, v211
	ds_read_b128 v[130:133], v0
	ds_read_b128 v[138:141], v0 offset:1024
	ds_read_b128 v[142:145], v0 offset:2048
	ds_read_b128 v[146:149], v0 offset:3072
	v_add_u32_e32 v0, 0x1c000, v211
	ds_read_b128 v[150:153], v0
	ds_read_b128 v[154:157], v0 offset:1024
	ds_read_b128 v[158:161], v0 offset:2048
	ds_read_b128 v[162:165], v0 offset:3072
	ds_read_b128 v[166:169], v212 offset:32768
	ds_read_b128 v[170:173], v212 offset:33792
	ds_read_b128 v[174:177], v212 offset:34816
	ds_read_b128 v[198:201], v212 offset:35840
	ds_read_b128 v[224:227], v212 offset:36864
	ds_read_b128 v[228:231], v212 offset:37888
	ds_read_b128 v[232:235], v212 offset:38912
	ds_read_b128 v[236:239], v212 offset:39936
	s_add_u32 s56, s56, 0x40000
	s_addc_u32 s57, s57, 0
	s_mov_b32 m0, s20
	s_nop 0
	global_load_lds_dwordx4 v178, s[56:57]
	s_mov_b32 m0, s21
	s_nop 0
	global_load_lds_dwordx4 v182, s[56:57]
	s_waitcnt vmcnt(8)
	s_waitcnt lgkmcnt(0)
	s_barrier
	s_setprio 1
	s_waitcnt lgkmcnt(7)
	v_mfma_f32_16x16x32_bf16 v[134:137], v[130:133], v[166:169], v[134:137]
	v_mfma_f32_16x16x32_bf16 v[122:125], v[142:145], v[166:169], v[122:125]
	s_waitcnt lgkmcnt(5)
	v_mfma_f32_16x16x32_bf16 v[110:113], v[130:133], v[174:177], v[110:113]
	v_mfma_f32_16x16x32_bf16 v[106:109], v[142:145], v[174:177], v[106:109]
	s_waitcnt lgkmcnt(3)
	v_mfma_f32_16x16x32_bf16 v[94:97], v[130:133], v[224:227], v[94:97]
	v_mfma_f32_16x16x32_bf16 v[90:93], v[142:145], v[224:227], v[90:93]
	s_waitcnt lgkmcnt(1)
	v_mfma_f32_16x16x32_bf16 v[78:81], v[130:133], v[232:235], v[78:81]
	v_mfma_f32_16x16x32_bf16 v[74:77], v[142:145], v[232:235], v[74:77]
	v_mfma_f32_16x16x32_bf16 v[134:137], v[138:141], v[170:173], v[134:137]
	v_mfma_f32_16x16x32_bf16 v[122:125], v[146:149], v[170:173], v[122:125]
	v_mfma_f32_16x16x32_bf16 v[110:113], v[138:141], v[198:201], v[110:113]
	v_mfma_f32_16x16x32_bf16 v[106:109], v[146:149], v[198:201], v[106:109]
	v_mfma_f32_16x16x32_bf16 v[94:97], v[138:141], v[228:231], v[94:97]
	v_mfma_f32_16x16x32_bf16 v[90:93], v[146:149], v[228:231], v[90:93]
	s_waitcnt lgkmcnt(0)
	v_mfma_f32_16x16x32_bf16 v[78:81], v[138:141], v[236:239], v[78:81]
	v_mfma_f32_16x16x32_bf16 v[74:77], v[146:149], v[236:239], v[74:77]
	s_setprio 0
	s_setprio 1
	v_mfma_f32_16x16x32_bf16 v[118:121], v[150:153], v[166:169], v[118:121]
	v_mfma_f32_16x16x32_bf16 v[114:117], v[158:161], v[166:169], v[114:117]
	v_mfma_f32_16x16x32_bf16 v[102:105], v[150:153], v[174:177], v[102:105]
	v_mfma_f32_16x16x32_bf16 v[98:101], v[158:161], v[174:177], v[98:101]
	v_mfma_f32_16x16x32_bf16 v[86:89], v[150:153], v[224:227], v[86:89]
	v_mfma_f32_16x16x32_bf16 v[82:85], v[158:161], v[224:227], v[82:85]
	v_mfma_f32_16x16x32_bf16 v[70:73], v[150:153], v[232:235], v[70:73]
	v_mfma_f32_16x16x32_bf16 v[66:69], v[158:161], v[232:235], v[66:69]
	v_mfma_f32_16x16x32_bf16 v[118:121], v[154:157], v[170:173], v[118:121]
	v_mfma_f32_16x16x32_bf16 v[114:117], v[162:165], v[170:173], v[114:117]
	v_mfma_f32_16x16x32_bf16 v[102:105], v[154:157], v[198:201], v[102:105]
	v_mfma_f32_16x16x32_bf16 v[98:101], v[162:165], v[198:201], v[98:101]
	v_mfma_f32_16x16x32_bf16 v[86:89], v[154:157], v[228:231], v[86:89]
	v_mfma_f32_16x16x32_bf16 v[82:85], v[162:165], v[228:231], v[82:85]
	v_mfma_f32_16x16x32_bf16 v[70:73], v[154:157], v[236:239], v[70:73]
	v_mfma_f32_16x16x32_bf16 v[66:69], v[162:165], v[236:239], v[66:69]
	s_setprio 0
	s_barrier
; #define PG8_STAGE(bufoff, gbase, voff) do { _Pragma("unroll") for (int _i = 0; _i < 2; ++_i) \
;         glds16_asm((const char*)(gbase) + (voff)[_i], ldsb + (unsigned)((bufoff) + _i * 8192)); } while (0)
; #define PG8_LDA(dst, b, h) do { _Pragma("unroll") for (int m = 0; m < 4; ++m) _Pragma("unroll") for (int k = 0; k < 2; ++k) dst[m][k] = *(const PG8_LAS bf16x8*)(lds + PG8_SA(b, h) + aoff + m * 2048 + k * 1024); } while (0)
; #define PG8_MMA(ai, bj, At, Bt) do { __builtin_amdgcn_s_setprio(1); _Pragma("unroll") for (int m = 0; m < 4; ++m) _Pragma("unroll") for (int n = 0; n < 2; ++n) _Pragma("unroll") for (int k = 0; k < 2; ++k) \
;         acc[ai][bj][m][n] = __builtin_amdgcn_mfma_f32_16x16x32_bf16(Bt[n][k], At[m][k], acc[ai][bj][m][n], 0, 0, 0); __builtin_amdgcn_s_setprio(0); } while (0)
; #define PG8_WAIT_V(n) asm volatile("s_waitcnt vmcnt(" #n ")" ::: "memory")
; #define PG8_WAIT_L(n) asm volatile("s_waitcnt lgkmcnt(" #n ")" ::: "memory")
; #define PG8_BAR __builtin_amdgcn_s_barrier()
; #define PG8_SCHED __builtin_amdgcn_sched_barrier(0)
; template <class Epi, class Sched, bool ALIGN_EPI = false, bool SP2 = false>
; __device__ __forceinline__ void gemm_phase(PG8_LAS unsigned char* lds, const Gemm g, const Sched& S, const Epi& E, int wave_u) {
;     ...
;         for (int t = 0; t < nt; t += 2) {
;     ...
;             PG8_LDA(At, 1, 1); PG8_STAGE(PG8_SB(1, 0), b3, voffB); PG8_STAGE(PG8_SB(1, 1), b3 + hstep, voffB); PG8_STAGE(PG8_SA(1, 0), a3, voffA);
;             PG8_WAIT_V(8); PG8_WAIT_L(0); PG8_BAR; PG8_MMA(1, 0, At, B0); PG8_MMA(1, 1, At, B1); PG8_BAR; PG8_SCHED;
	ds_read_b128 v[166:169], v212 offset:49152
	ds_read_b128 v[170:173], v212 offset:50176
	ds_read_b128 v[174:177], v212 offset:51200
	ds_read_b128 v[198:201], v212 offset:52224
	ds_read_b128 v[224:227], v212 offset:53248
	ds_read_b128 v[228:231], v212 offset:54272
	ds_read_b128 v[232:235], v212 offset:55296
	ds_read_b128 v[236:239], v212 offset:56320
	s_mov_b32 m0, s22
	s_nop 0
	global_load_lds_dwordx4 v180, s[48:49]
	s_add_u32 s44, s44, 0x40080
	s_mov_b32 m0, s23
	s_nop 0
	global_load_lds_dwordx4 v184, s[48:49]
	s_addc_u32 s45, s45, 0
	s_mov_b32 m0, s61
	s_nop 0
	global_load_lds_dwordx4 v180, s[44:45]
	s_mov_b32 m0, s26
	s_nop 0
	global_load_lds_dwordx4 v184, s[44:45]
	s_mov_b32 m0, s24
	s_nop 0
	global_load_lds_dwordx4 v178, s[46:47]
	s_mov_b32 m0, s25
	s_nop 0
	global_load_lds_dwordx4 v182, s[46:47]
	s_waitcnt vmcnt(8)
	s_waitcnt lgkmcnt(0)
	s_barrier
	s_setprio 1
	s_waitcnt lgkmcnt(7)
	v_mfma_f32_16x16x32_bf16 v[62:65], v[130:133], v[166:169], v[62:65]
	v_mfma_f32_16x16x32_bf16 v[58:61], v[142:145], v[166:169], v[58:61]
	s_waitcnt lgkmcnt(5)
	v_mfma_f32_16x16x32_bf16 v[46:49], v[130:133], v[174:177], v[46:49]
	v_mfma_f32_16x16x32_bf16 v[42:45], v[142:145], v[174:177], v[42:45]
	s_waitcnt lgkmcnt(3)
	v_mfma_f32_16x16x32_bf16 v[30:33], v[130:133], v[224:227], v[30:33]
	v_mfma_f32_16x16x32_bf16 v[26:29], v[142:145], v[224:227], v[26:29]
	s_waitcnt lgkmcnt(1)
	v_mfma_f32_16x16x32_bf16 v[14:17], v[130:133], v[232:235], v[14:17]
	v_mfma_f32_16x16x32_bf16 v[10:13], v[142:145], v[232:235], v[10:13]
	v_mfma_f32_16x16x32_bf16 v[62:65], v[138:141], v[170:173], v[62:65]
	v_mfma_f32_16x16x32_bf16 v[58:61], v[146:149], v[170:173], v[58:61]
	v_mfma_f32_16x16x32_bf16 v[46:49], v[138:141], v[198:201], v[46:49]
	v_mfma_f32_16x16x32_bf16 v[42:45], v[146:149], v[198:201], v[42:45]
	v_mfma_f32_16x16x32_bf16 v[30:33], v[138:141], v[228:231], v[30:33]
	v_mfma_f32_16x16x32_bf16 v[26:29], v[146:149], v[228:231], v[26:29]
	s_waitcnt lgkmcnt(0)
	v_mfma_f32_16x16x32_bf16 v[14:17], v[138:141], v[236:239], v[14:17]
	v_mfma_f32_16x16x32_bf16 v[10:13], v[146:149], v[236:239], v[10:13]
	s_setprio 0
	s_setprio 1
	v_mfma_f32_16x16x32_bf16 v[54:57], v[150:153], v[166:169], v[54:57]
	v_mfma_f32_16x16x32_bf16 v[50:53], v[158:161], v[166:169], v[50:53]
	v_mfma_f32_16x16x32_bf16 v[38:41], v[150:153], v[174:177], v[38:41]
	v_mfma_f32_16x16x32_bf16 v[34:37], v[158:161], v[174:177], v[34:37]
	v_mfma_f32_16x16x32_bf16 v[22:25], v[150:153], v[224:227], v[22:25]
	v_mfma_f32_16x16x32_bf16 v[18:21], v[158:161], v[224:227], v[18:21]
	v_mfma_f32_16x16x32_bf16 v[6:9], v[150:153], v[232:235], v[6:9]
	v_mfma_f32_16x16x32_bf16 v[2:5], v[158:161], v[232:235], v[2:5]
	v_mfma_f32_16x16x32_bf16 v[54:57], v[154:157], v[170:173], v[54:57]
	v_mfma_f32_16x16x32_bf16 v[50:53], v[162:165], v[170:173], v[50:53]
	v_mfma_f32_16x16x32_bf16 v[38:41], v[154:157], v[198:201], v[38:41]
	v_mfma_f32_16x16x32_bf16 v[34:37], v[162:165], v[198:201], v[34:37]
	v_mfma_f32_16x16x32_bf16 v[22:25], v[154:157], v[228:231], v[22:25]
	v_mfma_f32_16x16x32_bf16 v[18:21], v[162:165], v[228:231], v[18:21]
	v_mfma_f32_16x16x32_bf16 v[6:9], v[154:157], v[236:239], v[6:9]
	v_mfma_f32_16x16x32_bf16 v[2:5], v[162:165], v[236:239], v[2:5]
	s_setprio 0
	s_barrier
	s_add_i32 s52, s52, 2
	s_add_u32 s88, s88, 0x100
	s_addc_u32 s89, s89, 0
	s_add_u32 s40, s40, 0x100
	s_addc_u32 s41, s41, 0
	s_cmp_gt_u32 s52, 13
	s_cbranch_scc1 .LBB0_267

; #define PG8_STAGE(bufoff, gbase, voff) do { _Pragma("unroll") for (int _i = 0; _i < 2; ++_i) \
;         glds16_asm((const char*)(gbase) + (voff)[_i], ldsb + (unsigned)((bufoff) + _i * 8192)); } while (0)
; #define PG8_LDA(dst, b, h) do { _Pragma("unroll") for (int m = 0; m < 4; ++m) _Pragma("unroll") for (int k = 0; k < 2; ++k) dst[m][k] = *(const PG8_LAS bf16x8*)(lds + PG8_SA(b, h) + aoff + m * 2048 + k * 1024); } while (0)
; #define PG8_LDB(dst, b, h) do { _Pragma("unroll") for (int n = 0; n < 2; ++n) _Pragma("unroll") for (int k = 0; k < 2; ++k) dst[n][k] = *(const PG8_LAS bf16x8*)(lds + PG8_SB(b, h) + boff + n * 2048 + k * 1024); } while (0)
; #define PG8_MMA(ai, bj, At, Bt) do { __builtin_amdgcn_s_setprio(1); _Pragma("unroll") for (int m = 0; m < 4; ++m) _Pragma("unroll") for (int n = 0; n < 2; ++n) _Pragma("unroll") for (int k = 0; k < 2; ++k) \
;         acc[ai][bj][m][n] = __builtin_amdgcn_mfma_f32_16x16x32_bf16(Bt[n][k], At[m][k], acc[ai][bj][m][n], 0, 0, 0); __builtin_amdgcn_s_setprio(0); } while (0)
; #define PG8_WAIT_V(n) asm volatile("s_waitcnt vmcnt(" #n ")" ::: "memory")
; #define PG8_WAIT_L(n) asm volatile("s_waitcnt lgkmcnt(" #n ")" ::: "memory")
; #define PG8_BAR __builtin_amdgcn_s_barrier()
; #define PG8_SCHED __builtin_amdgcn_sched_barrier(0)
; template <class Epi, class Sched, bool ALIGN_EPI = false, bool SP2 = false>
; __device__ __forceinline__ void gemm_phase(PG8_LAS unsigned char* lds, const Gemm g, const Sched& S, const Epi& E, int wave_u) {
;     ...
;             PG8_LDB(B0, 0, 0); PG8_LDB(B1, 0, 1); PG8_SCHED; PG8_LDA(At, 0, 0); PG8_STAGE(PG8_SA(1, 1), a1 + hstep, voffA);
;             PG8_WAIT_V(8); PG8_WAIT_L(0); PG8_BAR; PG8_MMA(0, 0, At, B0); PG8_MMA(0, 1, At, B1); PG8_BAR; PG8_SCHED;
;             PG8_LDA(At, 0, 1); PG8_STAGE(PG8_SB(0, 0), b2, voffB); PG8_STAGE(PG8_SB(0, 1), b2 + hstep, voffB); PG8_STAGE(PG8_SA(0, 0), a2, voffA);
;             PG8_WAIT_V(8); PG8_WAIT_L(0); PG8_BAR; PG8_MMA(1, 0, At, B0); PG8_MMA(1, 1, At, B1); PG8_BAR; PG8_SCHED;
.LBB0_980:
	v_add_u32_e32 v0, 0x10000, v227
	ds_read_b128 v[62:65], v0
	ds_read_b128 v[74:77], v0 offset:1024
	ds_read_b128 v[90:93], v0 offset:2048
	ds_read_b128 v[98:101], v0 offset:3072
	v_add_u32_e32 v0, 0x14000, v227
	s_add_u32 s1, s64, 0xfffc0080
	ds_read_b128 v[114:117], v0
	ds_read_b128 v[122:125], v0 offset:1024
	ds_read_b128 v[138:141], v0 offset:2048
	ds_read_b128 v[146:149], v0 offset:3072
	s_addc_u32 s46, s65, -1
	s_and_b64 s[44:45], s[44:45], exec
	s_cselect_b32 s56, s53, s1
	s_cselect_b32 s57, s52, s46
	s_cselect_b32 s45, s19, s61
	s_cselect_b32 s44, s96, s60
	s_add_u32 s46, s56, 0x80
	s_addc_u32 s47, s57, 0
	s_add_u32 s48, s44, 0x80
	s_addc_u32 s49, s45, 0
	ds_read_b128 v[158:161], v228
	ds_read_b128 v[162:165], v228 offset:1024
	ds_read_b128 v[174:177], v228 offset:2048
	ds_read_b128 v[178:181], v228 offset:3072
	ds_read_b128 v[182:185], v228 offset:4096
	ds_read_b128 v[186:189], v228 offset:5120
	ds_read_b128 v[210:213], v228 offset:6144
	ds_read_b128 v[230:233], v228 offset:7168
	s_mov_b32 m0, s7
	s_nop 0
	global_load_lds_dwordx4 v198, s[64:65]
	s_mov_b32 m0, s75
	s_nop 0
	global_load_lds_dwordx4 v202, s[64:65]
	s_waitcnt vmcnt(8)
	s_waitcnt lgkmcnt(0)
	s_barrier
	s_setprio 1
	s_waitcnt lgkmcnt(7)
	v_mfma_f32_16x16x32_bf16 v[170:173], v[62:65], v[158:161], v[170:173]
	v_mfma_f32_16x16x32_bf16 v[166:169], v[90:93], v[158:161], v[166:169]
	s_waitcnt lgkmcnt(5)
	v_mfma_f32_16x16x32_bf16 v[142:145], v[62:65], v[174:177], v[142:145]
	v_mfma_f32_16x16x32_bf16 v[134:137], v[90:93], v[174:177], v[134:137]
	s_waitcnt lgkmcnt(3)
	v_mfma_f32_16x16x32_bf16 v[118:121], v[62:65], v[182:185], v[118:121]
	v_mfma_f32_16x16x32_bf16 v[110:113], v[90:93], v[182:185], v[110:113]
	s_waitcnt lgkmcnt(1)
	v_mfma_f32_16x16x32_bf16 v[94:97], v[62:65], v[210:213], v[94:97]
	v_mfma_f32_16x16x32_bf16 v[86:89], v[90:93], v[210:213], v[86:89]
	v_mfma_f32_16x16x32_bf16 v[170:173], v[74:77], v[162:165], v[170:173]
	v_mfma_f32_16x16x32_bf16 v[166:169], v[98:101], v[162:165], v[166:169]
	v_mfma_f32_16x16x32_bf16 v[142:145], v[74:77], v[178:181], v[142:145]
	v_mfma_f32_16x16x32_bf16 v[134:137], v[98:101], v[178:181], v[134:137]
	v_mfma_f32_16x16x32_bf16 v[118:121], v[74:77], v[186:189], v[118:121]
	v_mfma_f32_16x16x32_bf16 v[110:113], v[98:101], v[186:189], v[110:113]
	s_waitcnt lgkmcnt(0)
	v_mfma_f32_16x16x32_bf16 v[94:97], v[74:77], v[230:233], v[94:97]
	v_mfma_f32_16x16x32_bf16 v[86:89], v[98:101], v[230:233], v[86:89]
	s_setprio 0
	s_setprio 1
	v_mfma_f32_16x16x32_bf16 v[154:157], v[114:117], v[158:161], v[154:157]
	v_mfma_f32_16x16x32_bf16 v[150:153], v[138:141], v[158:161], v[150:153]
	v_mfma_f32_16x16x32_bf16 v[130:133], v[114:117], v[174:177], v[130:133]
	v_mfma_f32_16x16x32_bf16 v[126:129], v[138:141], v[174:177], v[126:129]
	v_mfma_f32_16x16x32_bf16 v[106:109], v[114:117], v[182:185], v[106:109]
	v_mfma_f32_16x16x32_bf16 v[102:105], v[138:141], v[182:185], v[102:105]
	v_mfma_f32_16x16x32_bf16 v[82:85], v[114:117], v[210:213], v[82:85]
	v_mfma_f32_16x16x32_bf16 v[78:81], v[138:141], v[210:213], v[78:81]
	v_mfma_f32_16x16x32_bf16 v[154:157], v[122:125], v[162:165], v[154:157]
	v_mfma_f32_16x16x32_bf16 v[150:153], v[146:149], v[162:165], v[150:153]
	v_mfma_f32_16x16x32_bf16 v[130:133], v[122:125], v[178:181], v[130:133]
	v_mfma_f32_16x16x32_bf16 v[126:129], v[146:149], v[178:181], v[126:129]
	v_mfma_f32_16x16x32_bf16 v[106:109], v[122:125], v[186:189], v[106:109]
	v_mfma_f32_16x16x32_bf16 v[102:105], v[146:149], v[186:189], v[102:105]
	v_mfma_f32_16x16x32_bf16 v[82:85], v[122:125], v[230:233], v[82:85]
	v_mfma_f32_16x16x32_bf16 v[78:81], v[146:149], v[230:233], v[78:81]
	s_setprio 0
	s_barrier
	ds_read_b128 v[158:161], v228 offset:16384
	ds_read_b128 v[162:165], v228 offset:17408
	ds_read_b128 v[174:177], v228 offset:18432
	ds_read_b128 v[178:181], v228 offset:19456
	ds_read_b128 v[182:185], v228 offset:20480
	ds_read_b128 v[186:189], v228 offset:21504
	ds_read_b128 v[210:213], v228 offset:22528
	ds_read_b128 v[230:233], v228 offset:23552
	s_mov_b32 m0, s35
	s_nop 0
	global_load_lds_dwordx4 v200, s[44:45]
	s_add_u32 vcc_lo, s44, 0x40000
	s_mov_b32 m0, s62
	s_nop 0
	global_load_lds_dwordx4 v204, s[44:45]
	s_addc_u32 vcc_hi, s45, 0
	s_mov_b32 m0, s63
	s_nop 0
	global_load_lds_dwordx4 v200, vcc
	s_mov_b32 m0, s86
	s_nop 0
	global_load_lds_dwordx4 v204, vcc
	s_mov_b32 m0, s2
	s_nop 0
	global_load_lds_dwordx4 v198, s[56:57]
	s_mov_b32 m0, s87
	s_nop 0
	global_load_lds_dwordx4 v202, s[56:57]
	s_waitcnt vmcnt(8)
	s_waitcnt lgkmcnt(0)
	s_barrier
; #define PG8_STAGE(bufoff, gbase, voff) do { _Pragma("unroll") for (int _i = 0; _i < 2; ++_i) \
;         glds16_asm((const char*)(gbase) + (voff)[_i], ldsb + (unsigned)((bufoff) + _i * 8192)); } while (0)
; #define PG8_LDA(dst, b, h) do { _Pragma("unroll") for (int m = 0; m < 4; ++m) _Pragma("unroll") for (int k = 0; k < 2; ++k) dst[m][k] = *(const PG8_LAS bf16x8*)(lds + PG8_SA(b, h) + aoff + m * 2048 + k * 1024); } while (0)
; #define PG8_LDB(dst, b, h) do { _Pragma("unroll") for (int n = 0; n < 2; ++n) _Pragma("unroll") for (int k = 0; k < 2; ++k) dst[n][k] = *(const PG8_LAS bf16x8*)(lds + PG8_SB(b, h) + boff + n * 2048 + k * 1024); } while (0)
; #define PG8_MMA(ai, bj, At, Bt) do { __builtin_amdgcn_s_setprio(1); _Pragma("unroll") for (int m = 0; m < 4; ++m) _Pragma("unroll") for (int n = 0; n < 2; ++n) _Pragma("unroll") for (int k = 0; k < 2; ++k) \
;         acc[ai][bj][m][n] = __builtin_amdgcn_mfma_f32_16x16x32_bf16(Bt[n][k], At[m][k], acc[ai][bj][m][n], 0, 0, 0); __builtin_amdgcn_s_setprio(0); } while (0)
; #define PG8_WAIT_V(n) asm volatile("s_waitcnt vmcnt(" #n ")" ::: "memory")
; #define PG8_WAIT_L(n) asm volatile("s_waitcnt lgkmcnt(" #n ")" ::: "memory")
; #define PG8_BAR __builtin_amdgcn_s_barrier()
; #define PG8_SCHED __builtin_amdgcn_sched_barrier(0)
; template <class Epi, class Sched, bool ALIGN_EPI = false, bool SP2 = false>
; __device__ __forceinline__ void gemm_phase(PG8_LAS unsigned char* lds, const Gemm g, const Sched& S, const Epi& E, int wave_u) {
;     ...
;             PG8_WAIT_V(8); PG8_WAIT_L(0); PG8_BAR; PG8_MMA(1, 0, At, B0); PG8_MMA(1, 1, At, B1); PG8_BAR; PG8_SCHED;
;             PG8_LDB(B0, 1, 0); PG8_LDB(B1, 1, 1); PG8_SCHED; PG8_LDA(At, 1, 0); PG8_STAGE(PG8_SA(0, 1), a2 + hstep, voffA);
;             PG8_WAIT_V(8); PG8_WAIT_L(0); PG8_BAR; PG8_MMA(0, 0, At, B0); PG8_MMA(0, 1, At, B1); PG8_BAR; PG8_SCHED;
	s_setprio 1
	s_waitcnt lgkmcnt(7)
	v_mfma_f32_16x16x32_bf16 v[70:73], v[62:65], v[158:161], v[70:73]
	v_mfma_f32_16x16x32_bf16 v[66:69], v[90:93], v[158:161], v[66:69]
	s_waitcnt lgkmcnt(5)
	v_mfma_f32_16x16x32_bf16 v[46:49], v[62:65], v[174:177], v[46:49]
	v_mfma_f32_16x16x32_bf16 v[42:45], v[90:93], v[174:177], v[42:45]
	s_waitcnt lgkmcnt(3)
	v_mfma_f32_16x16x32_bf16 v[30:33], v[62:65], v[182:185], v[30:33]
	v_mfma_f32_16x16x32_bf16 v[26:29], v[90:93], v[182:185], v[26:29]
	s_waitcnt lgkmcnt(1)
	v_mfma_f32_16x16x32_bf16 v[14:17], v[62:65], v[210:213], v[14:17]
	v_mfma_f32_16x16x32_bf16 v[10:13], v[90:93], v[210:213], v[10:13]
	v_mfma_f32_16x16x32_bf16 v[70:73], v[74:77], v[162:165], v[70:73]
	v_mfma_f32_16x16x32_bf16 v[66:69], v[98:101], v[162:165], v[66:69]
	v_mfma_f32_16x16x32_bf16 v[46:49], v[74:77], v[178:181], v[46:49]
	v_mfma_f32_16x16x32_bf16 v[42:45], v[98:101], v[178:181], v[42:45]
	v_mfma_f32_16x16x32_bf16 v[30:33], v[74:77], v[186:189], v[30:33]
	v_mfma_f32_16x16x32_bf16 v[26:29], v[98:101], v[186:189], v[26:29]
	s_waitcnt lgkmcnt(0)
	v_mfma_f32_16x16x32_bf16 v[14:17], v[74:77], v[230:233], v[14:17]
	v_mfma_f32_16x16x32_bf16 v[10:13], v[98:101], v[230:233], v[10:13]
	s_setprio 0
	s_setprio 1
	v_mfma_f32_16x16x32_bf16 v[58:61], v[114:117], v[158:161], v[58:61]
	v_mfma_f32_16x16x32_bf16 v[54:57], v[138:141], v[158:161], v[54:57]
	v_mfma_f32_16x16x32_bf16 v[38:41], v[114:117], v[174:177], v[38:41]
	v_mfma_f32_16x16x32_bf16 v[34:37], v[138:141], v[174:177], v[34:37]
	v_mfma_f32_16x16x32_bf16 v[22:25], v[114:117], v[182:185], v[22:25]
	v_mfma_f32_16x16x32_bf16 v[18:21], v[138:141], v[182:185], v[18:21]
	v_mfma_f32_16x16x32_bf16 v[6:9], v[114:117], v[210:213], v[6:9]
	v_mfma_f32_16x16x32_bf16 v[2:5], v[138:141], v[210:213], v[2:5]
	v_mfma_f32_16x16x32_bf16 v[58:61], v[122:125], v[162:165], v[58:61]
	v_mfma_f32_16x16x32_bf16 v[54:57], v[146:149], v[162:165], v[54:57]
	v_mfma_f32_16x16x32_bf16 v[38:41], v[122:125], v[178:181], v[38:41]
	v_mfma_f32_16x16x32_bf16 v[34:37], v[146:149], v[178:181], v[34:37]
	v_mfma_f32_16x16x32_bf16 v[22:25], v[122:125], v[186:189], v[22:25]
	v_mfma_f32_16x16x32_bf16 v[18:21], v[146:149], v[186:189], v[18:21]
	v_mfma_f32_16x16x32_bf16 v[6:9], v[122:125], v[230:233], v[6:9]
	v_mfma_f32_16x16x32_bf16 v[2:5], v[146:149], v[230:233], v[2:5]
	s_setprio 0
	s_barrier
	v_add_u32_e32 v0, 0x18000, v227
	ds_read_b128 v[62:65], v0
	ds_read_b128 v[74:77], v0 offset:1024
	ds_read_b128 v[90:93], v0 offset:2048
	ds_read_b128 v[98:101], v0 offset:3072
	v_add_u32_e32 v0, 0x1c000, v227
	ds_read_b128 v[114:117], v0
	ds_read_b128 v[122:125], v0 offset:1024
	ds_read_b128 v[138:141], v0 offset:2048
	ds_read_b128 v[146:149], v0 offset:3072
	ds_read_b128 v[158:161], v228 offset:32768
	ds_read_b128 v[162:165], v228 offset:33792
	ds_read_b128 v[174:177], v228 offset:34816
	ds_read_b128 v[178:181], v228 offset:35840
	ds_read_b128 v[182:185], v228 offset:36864
	ds_read_b128 v[186:189], v228 offset:37888
	ds_read_b128 v[210:213], v228 offset:38912
	ds_read_b128 v[230:233], v228 offset:39936
	s_add_u32 s56, s56, 0x40000
	s_addc_u32 s57, s57, 0
	s_mov_b32 m0, s88
	s_nop 0
	global_load_lds_dwordx4 v198, s[56:57]
	s_mov_b32 m0, s89
	s_nop 0
	global_load_lds_dwordx4 v202, s[56:57]
	s_waitcnt vmcnt(8)
	s_waitcnt lgkmcnt(0)
	s_barrier
	s_setprio 1
	s_waitcnt lgkmcnt(7)
	v_mfma_f32_16x16x32_bf16 v[170:173], v[62:65], v[158:161], v[170:173]
	v_mfma_f32_16x16x32_bf16 v[166:169], v[90:93], v[158:161], v[166:169]
	s_waitcnt lgkmcnt(5)
	v_mfma_f32_16x16x32_bf16 v[142:145], v[62:65], v[174:177], v[142:145]
	v_mfma_f32_16x16x32_bf16 v[134:137], v[90:93], v[174:177], v[134:137]
	s_waitcnt lgkmcnt(3)
	v_mfma_f32_16x16x32_bf16 v[118:121], v[62:65], v[182:185], v[118:121]
	v_mfma_f32_16x16x32_bf16 v[110:113], v[90:93], v[182:185], v[110:113]
	s_waitcnt lgkmcnt(1)
	v_mfma_f32_16x16x32_bf16 v[94:97], v[62:65], v[210:213], v[94:97]
	v_mfma_f32_16x16x32_bf16 v[86:89], v[90:93], v[210:213], v[86:89]
	v_mfma_f32_16x16x32_bf16 v[170:173], v[74:77], v[162:165], v[170:173]
	v_mfma_f32_16x16x32_bf16 v[166:169], v[98:101], v[162:165], v[166:169]
	v_mfma_f32_16x16x32_bf16 v[142:145], v[74:77], v[178:181], v[142:145]
	v_mfma_f32_16x16x32_bf16 v[134:137], v[98:101], v[178:181], v[134:137]
	v_mfma_f32_16x16x32_bf16 v[118:121], v[74:77], v[186:189], v[118:121]
	v_mfma_f32_16x16x32_bf16 v[110:113], v[98:101], v[186:189], v[110:113]
	s_waitcnt lgkmcnt(0)
	v_mfma_f32_16x16x32_bf16 v[94:97], v[74:77], v[230:233], v[94:97]
	v_mfma_f32_16x16x32_bf16 v[86:89], v[98:101], v[230:233], v[86:89]
	s_setprio 0
	s_setprio 1
	v_mfma_f32_16x16x32_bf16 v[154:157], v[114:117], v[158:161], v[154:157]
	v_mfma_f32_16x16x32_bf16 v[150:153], v[138:141], v[158:161], v[150:153]
	v_mfma_f32_16x16x32_bf16 v[130:133], v[114:117], v[174:177], v[130:133]
	v_mfma_f32_16x16x32_bf16 v[126:129], v[138:141], v[174:177], v[126:129]
	v_mfma_f32_16x16x32_bf16 v[106:109], v[114:117], v[182:185], v[106:109]
	v_mfma_f32_16x16x32_bf16 v[102:105], v[138:141], v[182:185], v[102:105]
	v_mfma_f32_16x16x32_bf16 v[82:85], v[114:117], v[210:213], v[82:85]
	v_mfma_f32_16x16x32_bf16 v[78:81], v[138:141], v[210:213], v[78:81]
	v_mfma_f32_16x16x32_bf16 v[154:157], v[122:125], v[162:165], v[154:157]
	v_mfma_f32_16x16x32_bf16 v[150:153], v[146:149], v[162:165], v[150:153]
	v_mfma_f32_16x16x32_bf16 v[130:133], v[122:125], v[178:181], v[130:133]
	v_mfma_f32_16x16x32_bf16 v[126:129], v[146:149], v[178:181], v[126:129]
	v_mfma_f32_16x16x32_bf16 v[106:109], v[122:125], v[186:189], v[106:109]
	v_mfma_f32_16x16x32_bf16 v[102:105], v[146:149], v[186:189], v[102:105]
	v_mfma_f32_16x16x32_bf16 v[82:85], v[122:125], v[230:233], v[82:85]
	v_mfma_f32_16x16x32_bf16 v[78:81], v[146:149], v[230:233], v[78:81]
	s_setprio 0
	s_barrier
; #define PG8_STAGE(bufoff, gbase, voff) do { _Pragma("unroll") for (int _i = 0; _i < 2; ++_i) \
;         glds16_asm((const char*)(gbase) + (voff)[_i], ldsb + (unsigned)((bufoff) + _i * 8192)); } while (0)
; #define PG8_LDA(dst, b, h) do { _Pragma("unroll") for (int m = 0; m < 4; ++m) _Pragma("unroll") for (int k = 0; k < 2; ++k) dst[m][k] = *(const PG8_LAS bf16x8*)(lds + PG8_SA(b, h) + aoff + m * 2048 + k * 1024); } while (0)
; #define PG8_MMA(ai, bj, At, Bt) do { __builtin_amdgcn_s_setprio(1); _Pragma("unroll") for (int m = 0; m < 4; ++m) _Pragma("unroll") for (int n = 0; n < 2; ++n) _Pragma("unroll") for (int k = 0; k < 2; ++k) \
;         acc[ai][bj][m][n] = __builtin_amdgcn_mfma_f32_16x16x32_bf16(Bt[n][k], At[m][k], acc[ai][bj][m][n], 0, 0, 0); __builtin_amdgcn_s_setprio(0); } while (0)
; #define PG8_WAIT_V(n) asm volatile("s_waitcnt vmcnt(" #n ")" ::: "memory")
; #define PG8_WAIT_L(n) asm volatile("s_waitcnt lgkmcnt(" #n ")" ::: "memory")
; #define PG8_BAR __builtin_amdgcn_s_barrier()
; #define PG8_SCHED __builtin_amdgcn_sched_barrier(0)
; template <class Epi, class Sched, bool ALIGN_EPI = false, bool SP2 = false>
; __device__ __forceinline__ void gemm_phase(PG8_LAS unsigned char* lds, const Gemm g, const Sched& S, const Epi& E, int wave_u) {
;     ...
;         for (int t = 0; t < nt; t += 2) {
;     ...
;             PG8_LDA(At, 1, 1); PG8_STAGE(PG8_SB(1, 0), b3, voffB); PG8_STAGE(PG8_SB(1, 1), b3 + hstep, voffB); PG8_STAGE(PG8_SA(1, 0), a3, voffA);
;             PG8_WAIT_V(8); PG8_WAIT_L(0); PG8_BAR; PG8_MMA(1, 0, At, B0); PG8_MMA(1, 1, At, B1); PG8_BAR; PG8_SCHED;
	ds_read_b128 v[158:161], v228 offset:49152
	ds_read_b128 v[162:165], v228 offset:50176
	ds_read_b128 v[174:177], v228 offset:51200
	ds_read_b128 v[178:181], v228 offset:52224
	ds_read_b128 v[182:185], v228 offset:53248
	ds_read_b128 v[186:189], v228 offset:54272
	ds_read_b128 v[210:213], v228 offset:55296
	ds_read_b128 v[230:233], v228 offset:56320
	s_mov_b32 m0, s90
	s_nop 0
	global_load_lds_dwordx4 v200, s[48:49]
	s_add_u32 s44, s44, 0x40080
	s_mov_b32 m0, s91
	s_nop 0
	global_load_lds_dwordx4 v204, s[48:49]
	s_addc_u32 s45, s45, 0
	s_mov_b32 m0, s66
	s_nop 0
	global_load_lds_dwordx4 v200, s[44:45]
	s_mov_b32 m0, s67
	s_nop 0
	global_load_lds_dwordx4 v204, s[44:45]
	s_mov_b32 m0, s40
	s_nop 0
	global_load_lds_dwordx4 v198, s[46:47]
	s_mov_b32 m0, s41
	s_nop 0
	global_load_lds_dwordx4 v202, s[46:47]
	s_waitcnt vmcnt(8)
	s_waitcnt lgkmcnt(0)
	s_barrier
	s_setprio 1
	s_waitcnt lgkmcnt(7)
	v_mfma_f32_16x16x32_bf16 v[70:73], v[62:65], v[158:161], v[70:73]
	v_mfma_f32_16x16x32_bf16 v[66:69], v[90:93], v[158:161], v[66:69]
	s_waitcnt lgkmcnt(5)
	v_mfma_f32_16x16x32_bf16 v[46:49], v[62:65], v[174:177], v[46:49]
	v_mfma_f32_16x16x32_bf16 v[42:45], v[90:93], v[174:177], v[42:45]
	s_waitcnt lgkmcnt(3)
	v_mfma_f32_16x16x32_bf16 v[30:33], v[62:65], v[182:185], v[30:33]
	v_mfma_f32_16x16x32_bf16 v[26:29], v[90:93], v[182:185], v[26:29]
	s_waitcnt lgkmcnt(1)
	v_mfma_f32_16x16x32_bf16 v[14:17], v[62:65], v[210:213], v[14:17]
	v_mfma_f32_16x16x32_bf16 v[10:13], v[90:93], v[210:213], v[10:13]
	v_mfma_f32_16x16x32_bf16 v[70:73], v[74:77], v[162:165], v[70:73]
	v_mfma_f32_16x16x32_bf16 v[66:69], v[98:101], v[162:165], v[66:69]
	v_mfma_f32_16x16x32_bf16 v[46:49], v[74:77], v[178:181], v[46:49]
	v_mfma_f32_16x16x32_bf16 v[42:45], v[98:101], v[178:181], v[42:45]
	v_mfma_f32_16x16x32_bf16 v[30:33], v[74:77], v[186:189], v[30:33]
	v_mfma_f32_16x16x32_bf16 v[26:29], v[98:101], v[186:189], v[26:29]
	s_waitcnt lgkmcnt(0)
	v_mfma_f32_16x16x32_bf16 v[14:17], v[74:77], v[230:233], v[14:17]
	v_mfma_f32_16x16x32_bf16 v[10:13], v[98:101], v[230:233], v[10:13]
	s_setprio 0
	s_setprio 1
	v_mfma_f32_16x16x32_bf16 v[58:61], v[114:117], v[158:161], v[58:61]
	v_mfma_f32_16x16x32_bf16 v[54:57], v[138:141], v[158:161], v[54:57]
	v_mfma_f32_16x16x32_bf16 v[38:41], v[114:117], v[174:177], v[38:41]
	v_mfma_f32_16x16x32_bf16 v[34:37], v[138:141], v[174:177], v[34:37]
	v_mfma_f32_16x16x32_bf16 v[22:25], v[114:117], v[182:185], v[22:25]
	v_mfma_f32_16x16x32_bf16 v[18:21], v[138:141], v[182:185], v[18:21]
	v_mfma_f32_16x16x32_bf16 v[6:9], v[114:117], v[210:213], v[6:9]
	v_mfma_f32_16x16x32_bf16 v[2:5], v[138:141], v[210:213], v[2:5]
	v_mfma_f32_16x16x32_bf16 v[58:61], v[122:125], v[162:165], v[58:61]
	v_mfma_f32_16x16x32_bf16 v[54:57], v[146:149], v[162:165], v[54:57]
	v_mfma_f32_16x16x32_bf16 v[38:41], v[122:125], v[178:181], v[38:41]
	v_mfma_f32_16x16x32_bf16 v[34:37], v[146:149], v[178:181], v[34:37]
	v_mfma_f32_16x16x32_bf16 v[22:25], v[122:125], v[186:189], v[22:25]
	v_mfma_f32_16x16x32_bf16 v[18:21], v[146:149], v[186:189], v[18:21]
	v_mfma_f32_16x16x32_bf16 v[6:9], v[122:125], v[230:233], v[6:9]
	v_mfma_f32_16x16x32_bf16 v[2:5], v[146:149], v[230:233], v[2:5]
	s_setprio 0
	s_barrier
	s_add_i32 s84, s84, 2
	s_add_u32 s64, s64, 0x100
	s_addc_u32 s65, s65, 0
	s_add_u32 s60, s60, 0x100
	s_addc_u32 s61, s61, 0
	s_cmp_gt_u32 s84, 13
	s_cbranch_scc1 .LBB0_983

; #define PG8_STAGE(bufoff, gbase, voff) do { _Pragma("unroll") for (int _i = 0; _i < 2; ++_i) \
;         glds16_asm((const char*)(gbase) + (voff)[_i], ldsb + (unsigned)((bufoff) + _i * 8192)); } while (0)
; #define PG8_LDA(dst, b, h) do { _Pragma("unroll") for (int m = 0; m < 4; ++m) _Pragma("unroll") for (int k = 0; k < 2; ++k) dst[m][k] = *(const PG8_LAS bf16x8*)(lds + PG8_SA(b, h) + aoff + m * 2048 + k * 1024); } while (0)
; #define PG8_LDB(dst, b, h) do { _Pragma("unroll") for (int n = 0; n < 2; ++n) _Pragma("unroll") for (int k = 0; k < 2; ++k) dst[n][k] = *(const PG8_LAS bf16x8*)(lds + PG8_SB(b, h) + boff + n * 2048 + k * 1024); } while (0)
; #define PG8_MMA(ai, bj, At, Bt) do { __builtin_amdgcn_s_setprio(1); _Pragma("unroll") for (int m = 0; m < 4; ++m) _Pragma("unroll") for (int n = 0; n < 2; ++n) _Pragma("unroll") for (int k = 0; k < 2; ++k) \
;         acc[ai][bj][m][n] = __builtin_amdgcn_mfma_f32_16x16x32_bf16(Bt[n][k], At[m][k], acc[ai][bj][m][n], 0, 0, 0); __builtin_amdgcn_s_setprio(0); } while (0)
; #define PG8_WAIT_V(n) asm volatile("s_waitcnt vmcnt(" #n ")" ::: "memory")
; #define PG8_WAIT_L(n) asm volatile("s_waitcnt lgkmcnt(" #n ")" ::: "memory")
; #define PG8_BAR __builtin_amdgcn_s_barrier()
; #define PG8_SCHED __builtin_amdgcn_sched_barrier(0)
; template <class Epi, class Sched, bool ALIGN_EPI = false, bool SP2 = false>
; __device__ __forceinline__ void gemm_phase(PG8_LAS unsigned char* lds, const Gemm g, const Sched& S, const Epi& E, int wave_u) {
;     ...
;             PG8_LDB(B0, 0, 0); PG8_LDB(B1, 0, 1); PG8_SCHED; PG8_LDA(At, 0, 0); PG8_STAGE(PG8_SA(1, 1), a1 + hstep, voffA);
;             PG8_WAIT_V(8); PG8_WAIT_L(0); PG8_BAR; PG8_MMA(0, 0, At, B0); PG8_MMA(0, 1, At, B1); PG8_BAR; PG8_SCHED;
;             PG8_LDA(At, 0, 1); PG8_STAGE(PG8_SB(0, 0), b2, voffB); PG8_STAGE(PG8_SB(0, 1), b2 + hstep, voffB); PG8_STAGE(PG8_SA(0, 0), a2, voffA);
;             PG8_WAIT_V(8); PG8_WAIT_L(0); PG8_BAR; PG8_MMA(1, 0, At, B0); PG8_MMA(1, 1, At, B1); PG8_BAR; PG8_SCHED;
.LBB0_1175:
	v_add_u32_e32 v146, 0x10000, v177
	v_add_u32_e32 v179, 0x14000, v177
	s_add_u32 s44, s60, 0xfffc0080
	ds_read_b128 v[134:137], v146
	ds_read_b128 v[138:141], v146 offset:1024
	ds_read_b128 v[142:145], v146 offset:2048
	ds_read_b128 v[146:149], v146 offset:3072
	ds_read_b128 v[150:153], v179
	ds_read_b128 v[154:157], v179 offset:1024
	ds_read_b128 v[158:161], v179 offset:2048
	ds_read_b128 v[180:183], v179 offset:3072
	s_addc_u32 s45, s61, -1
	s_and_b64 s[34:35], s[34:35], exec
	s_cselect_b32 s48, s91, s44
	s_cselect_b32 s49, s90, s45
	s_cselect_b32 s35, s21, s85
	s_cselect_b32 s34, s96, s84
	s_add_u32 s44, s48, 0x80
	s_addc_u32 s45, s49, 0
	s_add_u32 s46, s34, 0x80
	s_addc_u32 s47, s35, 0
	ds_read_b128 v[184:187], v178
	ds_read_b128 v[198:201], v178 offset:1024
	ds_read_b128 v[202:205], v178 offset:2048
	ds_read_b128 v[206:209], v178 offset:3072
	ds_read_b128 v[210:213], v178 offset:4096
	ds_read_b128 v[224:227], v178 offset:5120
	ds_read_b128 v[228:231], v178 offset:6144
	ds_read_b128 v[232:235], v178 offset:7168
	s_mov_b32 m0, s87
	s_nop 0
	global_load_lds_dwordx4 v168, s[60:61]
	s_mov_b32 m0, s88
	s_nop 0
	global_load_lds_dwordx4 v164, s[60:61]
	s_waitcnt vmcnt(8)
	s_waitcnt lgkmcnt(0)
	s_barrier
	s_setprio 1
	s_waitcnt lgkmcnt(7)
	v_mfma_f32_16x16x32_bf16 v[122:125], v[134:137], v[184:187], v[122:125]
	v_mfma_f32_16x16x32_bf16 v[114:117], v[142:145], v[184:187], v[114:117]
	s_waitcnt lgkmcnt(5)
	v_mfma_f32_16x16x32_bf16 v[106:109], v[134:137], v[202:205], v[106:109]
	v_mfma_f32_16x16x32_bf16 v[98:101], v[142:145], v[202:205], v[98:101]
	s_waitcnt lgkmcnt(3)
	v_mfma_f32_16x16x32_bf16 v[90:93], v[134:137], v[210:213], v[90:93]
	v_mfma_f32_16x16x32_bf16 v[82:85], v[142:145], v[210:213], v[82:85]
	s_waitcnt lgkmcnt(1)
	v_mfma_f32_16x16x32_bf16 v[74:77], v[134:137], v[228:231], v[74:77]
	v_mfma_f32_16x16x32_bf16 v[66:69], v[142:145], v[228:231], v[66:69]
	v_mfma_f32_16x16x32_bf16 v[122:125], v[138:141], v[198:201], v[122:125]
	v_mfma_f32_16x16x32_bf16 v[114:117], v[146:149], v[198:201], v[114:117]
	v_mfma_f32_16x16x32_bf16 v[106:109], v[138:141], v[206:209], v[106:109]
	v_mfma_f32_16x16x32_bf16 v[98:101], v[146:149], v[206:209], v[98:101]
	v_mfma_f32_16x16x32_bf16 v[90:93], v[138:141], v[224:227], v[90:93]
	v_mfma_f32_16x16x32_bf16 v[82:85], v[146:149], v[224:227], v[82:85]
	s_waitcnt lgkmcnt(0)
	v_mfma_f32_16x16x32_bf16 v[74:77], v[138:141], v[232:235], v[74:77]
	v_mfma_f32_16x16x32_bf16 v[66:69], v[146:149], v[232:235], v[66:69]
	s_setprio 0
	s_setprio 1
	v_mfma_f32_16x16x32_bf16 v[126:129], v[150:153], v[184:187], v[126:129]
	v_mfma_f32_16x16x32_bf16 v[118:121], v[158:161], v[184:187], v[118:121]
	v_mfma_f32_16x16x32_bf16 v[110:113], v[150:153], v[202:205], v[110:113]
	v_mfma_f32_16x16x32_bf16 v[102:105], v[158:161], v[202:205], v[102:105]
	v_mfma_f32_16x16x32_bf16 v[94:97], v[150:153], v[210:213], v[94:97]
	v_mfma_f32_16x16x32_bf16 v[86:89], v[158:161], v[210:213], v[86:89]
	v_mfma_f32_16x16x32_bf16 v[78:81], v[150:153], v[228:231], v[78:81]
	v_mfma_f32_16x16x32_bf16 v[70:73], v[158:161], v[228:231], v[70:73]
	v_mfma_f32_16x16x32_bf16 v[126:129], v[154:157], v[198:201], v[126:129]
	v_mfma_f32_16x16x32_bf16 v[118:121], v[180:183], v[198:201], v[118:121]
	v_mfma_f32_16x16x32_bf16 v[110:113], v[154:157], v[206:209], v[110:113]
	v_mfma_f32_16x16x32_bf16 v[102:105], v[180:183], v[206:209], v[102:105]
	v_mfma_f32_16x16x32_bf16 v[94:97], v[154:157], v[224:227], v[94:97]
	v_mfma_f32_16x16x32_bf16 v[86:89], v[180:183], v[224:227], v[86:89]
	v_mfma_f32_16x16x32_bf16 v[78:81], v[154:157], v[232:235], v[78:81]
	v_mfma_f32_16x16x32_bf16 v[70:73], v[180:183], v[232:235], v[70:73]
	s_setprio 0
	s_barrier
	ds_read_b128 v[184:187], v178 offset:16384
	ds_read_b128 v[198:201], v178 offset:17408
	ds_read_b128 v[202:205], v178 offset:18432
	ds_read_b128 v[206:209], v178 offset:19456
	ds_read_b128 v[210:213], v178 offset:20480
	ds_read_b128 v[224:227], v178 offset:21504
	ds_read_b128 v[228:231], v178 offset:22528
	ds_read_b128 v[232:235], v178 offset:23552
	s_mov_b32 m0, s52
	s_nop 0
	global_load_lds_dwordx4 v166, s[34:35]
	s_mov_b32 m0, s58
	s_nop 0
	global_load_lds_dwordx4 v162, s[34:35]
	s_add_u32 vcc_lo, s34, 0x40000
	s_addc_u32 vcc_hi, s35, 0
	s_mov_b32 m0, s59
	s_nop 0
	global_load_lds_dwordx4 v166, vcc
	s_mov_b32 m0, s62
	s_nop 0
	global_load_lds_dwordx4 v162, vcc
	s_mov_b32 m0, s7
	s_nop 0
	global_load_lds_dwordx4 v168, s[48:49]
	s_mov_b32 m0, s63
	s_nop 0
	global_load_lds_dwordx4 v164, s[48:49]
	s_waitcnt vmcnt(8)
	s_waitcnt lgkmcnt(0)
	s_barrier
; #define PG8_STAGE(bufoff, gbase, voff) do { _Pragma("unroll") for (int _i = 0; _i < 2; ++_i) \
;         glds16_asm((const char*)(gbase) + (voff)[_i], ldsb + (unsigned)((bufoff) + _i * 8192)); } while (0)
; #define PG8_LDA(dst, b, h) do { _Pragma("unroll") for (int m = 0; m < 4; ++m) _Pragma("unroll") for (int k = 0; k < 2; ++k) dst[m][k] = *(const PG8_LAS bf16x8*)(lds + PG8_SA(b, h) + aoff + m * 2048 + k * 1024); } while (0)
; #define PG8_LDB(dst, b, h) do { _Pragma("unroll") for (int n = 0; n < 2; ++n) _Pragma("unroll") for (int k = 0; k < 2; ++k) dst[n][k] = *(const PG8_LAS bf16x8*)(lds + PG8_SB(b, h) + boff + n * 2048 + k * 1024); } while (0)
; #define PG8_MMA(ai, bj, At, Bt) do { __builtin_amdgcn_s_setprio(1); _Pragma("unroll") for (int m = 0; m < 4; ++m) _Pragma("unroll") for (int n = 0; n < 2; ++n) _Pragma("unroll") for (int k = 0; k < 2; ++k) \
;         acc[ai][bj][m][n] = __builtin_amdgcn_mfma_f32_16x16x32_bf16(Bt[n][k], At[m][k], acc[ai][bj][m][n], 0, 0, 0); __builtin_amdgcn_s_setprio(0); } while (0)
; #define PG8_WAIT_V(n) asm volatile("s_waitcnt vmcnt(" #n ")" ::: "memory")
; #define PG8_WAIT_L(n) asm volatile("s_waitcnt lgkmcnt(" #n ")" ::: "memory")
; #define PG8_BAR __builtin_amdgcn_s_barrier()
; #define PG8_SCHED __builtin_amdgcn_sched_barrier(0)
; template <class Epi, class Sched, bool ALIGN_EPI = false, bool SP2 = false>
; __device__ __forceinline__ void gemm_phase(PG8_LAS unsigned char* lds, const Gemm g, const Sched& S, const Epi& E, int wave_u) {
;     ...
;             PG8_WAIT_V(8); PG8_WAIT_L(0); PG8_BAR; PG8_MMA(1, 0, At, B0); PG8_MMA(1, 1, At, B1); PG8_BAR; PG8_SCHED;
;             PG8_LDB(B0, 1, 0); PG8_LDB(B1, 1, 1); PG8_SCHED; PG8_LDA(At, 1, 0); PG8_STAGE(PG8_SA(0, 1), a2 + hstep, voffA);
;             PG8_WAIT_V(8); PG8_WAIT_L(0); PG8_BAR; PG8_MMA(0, 0, At, B0); PG8_MMA(0, 1, At, B1); PG8_BAR; PG8_SCHED;
	s_setprio 1
	s_waitcnt lgkmcnt(7)
	v_mfma_f32_16x16x32_bf16 v[58:61], v[134:137], v[184:187], v[58:61]
	v_mfma_f32_16x16x32_bf16 v[50:53], v[142:145], v[184:187], v[50:53]
	s_waitcnt lgkmcnt(5)
	v_mfma_f32_16x16x32_bf16 v[42:45], v[134:137], v[202:205], v[42:45]
	v_mfma_f32_16x16x32_bf16 v[34:37], v[142:145], v[202:205], v[34:37]
	s_waitcnt lgkmcnt(3)
	v_mfma_f32_16x16x32_bf16 v[26:29], v[134:137], v[210:213], v[26:29]
	v_mfma_f32_16x16x32_bf16 v[18:21], v[142:145], v[210:213], v[18:21]
	s_waitcnt lgkmcnt(1)
	v_mfma_f32_16x16x32_bf16 v[10:13], v[134:137], v[228:231], v[10:13]
	v_mfma_f32_16x16x32_bf16 v[2:5], v[142:145], v[228:231], v[2:5]
	v_mfma_f32_16x16x32_bf16 v[58:61], v[138:141], v[198:201], v[58:61]
	v_mfma_f32_16x16x32_bf16 v[50:53], v[146:149], v[198:201], v[50:53]
	v_mfma_f32_16x16x32_bf16 v[42:45], v[138:141], v[206:209], v[42:45]
	v_mfma_f32_16x16x32_bf16 v[34:37], v[146:149], v[206:209], v[34:37]
	v_mfma_f32_16x16x32_bf16 v[26:29], v[138:141], v[224:227], v[26:29]
	v_mfma_f32_16x16x32_bf16 v[18:21], v[146:149], v[224:227], v[18:21]
	s_waitcnt lgkmcnt(0)
	v_mfma_f32_16x16x32_bf16 v[10:13], v[138:141], v[232:235], v[10:13]
	v_mfma_f32_16x16x32_bf16 v[2:5], v[146:149], v[232:235], v[2:5]
	s_setprio 0
	s_setprio 1
	v_mfma_f32_16x16x32_bf16 v[62:65], v[150:153], v[184:187], v[62:65]
	v_mfma_f32_16x16x32_bf16 v[54:57], v[158:161], v[184:187], v[54:57]
	v_mfma_f32_16x16x32_bf16 v[46:49], v[150:153], v[202:205], v[46:49]
	v_mfma_f32_16x16x32_bf16 v[38:41], v[158:161], v[202:205], v[38:41]
	v_mfma_f32_16x16x32_bf16 v[30:33], v[150:153], v[210:213], v[30:33]
	v_mfma_f32_16x16x32_bf16 v[22:25], v[158:161], v[210:213], v[22:25]
	v_mfma_f32_16x16x32_bf16 v[14:17], v[150:153], v[228:231], v[14:17]
	v_mfma_f32_16x16x32_bf16 v[6:9], v[158:161], v[228:231], v[6:9]
	v_mfma_f32_16x16x32_bf16 v[62:65], v[154:157], v[198:201], v[62:65]
	v_mfma_f32_16x16x32_bf16 v[54:57], v[180:183], v[198:201], v[54:57]
	v_mfma_f32_16x16x32_bf16 v[46:49], v[154:157], v[206:209], v[46:49]
	v_mfma_f32_16x16x32_bf16 v[38:41], v[180:183], v[206:209], v[38:41]
	v_mfma_f32_16x16x32_bf16 v[30:33], v[154:157], v[224:227], v[30:33]
	v_mfma_f32_16x16x32_bf16 v[22:25], v[180:183], v[224:227], v[22:25]
	v_mfma_f32_16x16x32_bf16 v[14:17], v[154:157], v[232:235], v[14:17]
	v_mfma_f32_16x16x32_bf16 v[6:9], v[180:183], v[232:235], v[6:9]
	s_setprio 0
	s_barrier
	v_add_u32_e32 v146, 0x18000, v177
	v_add_u32_e32 v179, 0x1c000, v177
	ds_read_b128 v[134:137], v146
	ds_read_b128 v[138:141], v146 offset:1024
	ds_read_b128 v[142:145], v146 offset:2048
	ds_read_b128 v[146:149], v146 offset:3072
	ds_read_b128 v[150:153], v179
	ds_read_b128 v[154:157], v179 offset:1024
	ds_read_b128 v[158:161], v179 offset:2048
	ds_read_b128 v[180:183], v179 offset:3072
	ds_read_b128 v[184:187], v178 offset:32768
	ds_read_b128 v[198:201], v178 offset:33792
	ds_read_b128 v[202:205], v178 offset:34816
	ds_read_b128 v[206:209], v178 offset:35840
	ds_read_b128 v[210:213], v178 offset:36864
	ds_read_b128 v[224:227], v178 offset:37888
	ds_read_b128 v[228:231], v178 offset:38912
	ds_read_b128 v[232:235], v178 offset:39936
	s_add_u32 s48, s48, 0x40000
	s_addc_u32 s49, s49, 0
	s_mov_b32 m0, s64
	s_nop 0
	global_load_lds_dwordx4 v168, s[48:49]
	s_mov_b32 m0, s65
	s_nop 0
	global_load_lds_dwordx4 v164, s[48:49]
	s_waitcnt vmcnt(8)
	s_waitcnt lgkmcnt(0)
	s_barrier
	s_setprio 1
	s_waitcnt lgkmcnt(7)
	v_mfma_f32_16x16x32_bf16 v[122:125], v[134:137], v[184:187], v[122:125]
	v_mfma_f32_16x16x32_bf16 v[114:117], v[142:145], v[184:187], v[114:117]
	s_waitcnt lgkmcnt(5)
	v_mfma_f32_16x16x32_bf16 v[106:109], v[134:137], v[202:205], v[106:109]
	v_mfma_f32_16x16x32_bf16 v[98:101], v[142:145], v[202:205], v[98:101]
	s_waitcnt lgkmcnt(3)
	v_mfma_f32_16x16x32_bf16 v[90:93], v[134:137], v[210:213], v[90:93]
	v_mfma_f32_16x16x32_bf16 v[82:85], v[142:145], v[210:213], v[82:85]
	s_waitcnt lgkmcnt(1)
	v_mfma_f32_16x16x32_bf16 v[74:77], v[134:137], v[228:231], v[74:77]
	v_mfma_f32_16x16x32_bf16 v[66:69], v[142:145], v[228:231], v[66:69]
	v_mfma_f32_16x16x32_bf16 v[122:125], v[138:141], v[198:201], v[122:125]
	v_mfma_f32_16x16x32_bf16 v[114:117], v[146:149], v[198:201], v[114:117]
	v_mfma_f32_16x16x32_bf16 v[106:109], v[138:141], v[206:209], v[106:109]
	v_mfma_f32_16x16x32_bf16 v[98:101], v[146:149], v[206:209], v[98:101]
	v_mfma_f32_16x16x32_bf16 v[90:93], v[138:141], v[224:227], v[90:93]
	v_mfma_f32_16x16x32_bf16 v[82:85], v[146:149], v[224:227], v[82:85]
	s_waitcnt lgkmcnt(0)
	v_mfma_f32_16x16x32_bf16 v[74:77], v[138:141], v[232:235], v[74:77]
	v_mfma_f32_16x16x32_bf16 v[66:69], v[146:149], v[232:235], v[66:69]
	s_setprio 0
	s_setprio 1
	v_mfma_f32_16x16x32_bf16 v[126:129], v[150:153], v[184:187], v[126:129]
	v_mfma_f32_16x16x32_bf16 v[118:121], v[158:161], v[184:187], v[118:121]
	v_mfma_f32_16x16x32_bf16 v[110:113], v[150:153], v[202:205], v[110:113]
	v_mfma_f32_16x16x32_bf16 v[102:105], v[158:161], v[202:205], v[102:105]
	v_mfma_f32_16x16x32_bf16 v[94:97], v[150:153], v[210:213], v[94:97]
	v_mfma_f32_16x16x32_bf16 v[86:89], v[158:161], v[210:213], v[86:89]
	v_mfma_f32_16x16x32_bf16 v[78:81], v[150:153], v[228:231], v[78:81]
	v_mfma_f32_16x16x32_bf16 v[70:73], v[158:161], v[228:231], v[70:73]
	v_mfma_f32_16x16x32_bf16 v[126:129], v[154:157], v[198:201], v[126:129]
	v_mfma_f32_16x16x32_bf16 v[118:121], v[180:183], v[198:201], v[118:121]
	v_mfma_f32_16x16x32_bf16 v[110:113], v[154:157], v[206:209], v[110:113]
	v_mfma_f32_16x16x32_bf16 v[102:105], v[180:183], v[206:209], v[102:105]
	v_mfma_f32_16x16x32_bf16 v[94:97], v[154:157], v[224:227], v[94:97]
	v_mfma_f32_16x16x32_bf16 v[86:89], v[180:183], v[224:227], v[86:89]
	v_mfma_f32_16x16x32_bf16 v[78:81], v[154:157], v[232:235], v[78:81]
	v_mfma_f32_16x16x32_bf16 v[70:73], v[180:183], v[232:235], v[70:73]
	s_setprio 0
	s_barrier
; #define PG8_STAGE(bufoff, gbase, voff) do { _Pragma("unroll") for (int _i = 0; _i < 2; ++_i) \
;         glds16_asm((const char*)(gbase) + (voff)[_i], ldsb + (unsigned)((bufoff) + _i * 8192)); } while (0)
; #define PG8_LDA(dst, b, h) do { _Pragma("unroll") for (int m = 0; m < 4; ++m) _Pragma("unroll") for (int k = 0; k < 2; ++k) dst[m][k] = *(const PG8_LAS bf16x8*)(lds + PG8_SA(b, h) + aoff + m * 2048 + k * 1024); } while (0)
; #define PG8_MMA(ai, bj, At, Bt) do { __builtin_amdgcn_s_setprio(1); _Pragma("unroll") for (int m = 0; m < 4; ++m) _Pragma("unroll") for (int n = 0; n < 2; ++n) _Pragma("unroll") for (int k = 0; k < 2; ++k) \
;         acc[ai][bj][m][n] = __builtin_amdgcn_mfma_f32_16x16x32_bf16(Bt[n][k], At[m][k], acc[ai][bj][m][n], 0, 0, 0); __builtin_amdgcn_s_setprio(0); } while (0)
; #define PG8_WAIT_V(n) asm volatile("s_waitcnt vmcnt(" #n ")" ::: "memory")
; #define PG8_WAIT_L(n) asm volatile("s_waitcnt lgkmcnt(" #n ")" ::: "memory")
; #define PG8_BAR __builtin_amdgcn_s_barrier()
; #define PG8_SCHED __builtin_amdgcn_sched_barrier(0)
; template <class Epi, class Sched, bool ALIGN_EPI = false, bool SP2 = false>
; __device__ __forceinline__ void gemm_phase(PG8_LAS unsigned char* lds, const Gemm g, const Sched& S, const Epi& E, int wave_u) {
;     ...
;         for (int t = 0; t < nt; t += 2) {
;     ...
;             PG8_LDA(At, 1, 1); PG8_STAGE(PG8_SB(1, 0), b3, voffB); PG8_STAGE(PG8_SB(1, 1), b3 + hstep, voffB); PG8_STAGE(PG8_SA(1, 0), a3, voffA);
;             PG8_WAIT_V(8); PG8_WAIT_L(0); PG8_BAR; PG8_MMA(1, 0, At, B0); PG8_MMA(1, 1, At, B1); PG8_BAR; PG8_SCHED;
	ds_read_b128 v[184:187], v178 offset:49152
	ds_read_b128 v[198:201], v178 offset:50176
	ds_read_b128 v[202:205], v178 offset:51200
	ds_read_b128 v[206:209], v178 offset:52224
	ds_read_b128 v[210:213], v178 offset:53248
	ds_read_b128 v[224:227], v178 offset:54272
	ds_read_b128 v[228:231], v178 offset:55296
	ds_read_b128 v[232:235], v178 offset:56320
	s_mov_b32 m0, s66
	s_nop 0
	global_load_lds_dwordx4 v166, s[46:47]
	s_add_u32 s34, s34, 0x40080
	s_mov_b32 m0, s67
	s_nop 0
	global_load_lds_dwordx4 v162, s[46:47]
	s_addc_u32 s35, s35, 0
	s_mov_b32 m0, s79
	s_nop 0
	global_load_lds_dwordx4 v166, s[34:35]
	s_mov_b32 m0, s86
	s_nop 0
	global_load_lds_dwordx4 v162, s[34:35]
	s_mov_b32 m0, s75
	s_nop 0
	global_load_lds_dwordx4 v168, s[44:45]
	s_mov_b32 m0, s78
	s_nop 0
	global_load_lds_dwordx4 v164, s[44:45]
	s_waitcnt vmcnt(8)
	s_waitcnt lgkmcnt(0)
	s_barrier
	s_setprio 1
	s_waitcnt lgkmcnt(7)
	v_mfma_f32_16x16x32_bf16 v[58:61], v[134:137], v[184:187], v[58:61]
	v_mfma_f32_16x16x32_bf16 v[50:53], v[142:145], v[184:187], v[50:53]
	s_waitcnt lgkmcnt(5)
	v_mfma_f32_16x16x32_bf16 v[42:45], v[134:137], v[202:205], v[42:45]
	v_mfma_f32_16x16x32_bf16 v[34:37], v[142:145], v[202:205], v[34:37]
	s_waitcnt lgkmcnt(3)
	v_mfma_f32_16x16x32_bf16 v[26:29], v[134:137], v[210:213], v[26:29]
	v_mfma_f32_16x16x32_bf16 v[18:21], v[142:145], v[210:213], v[18:21]
	s_waitcnt lgkmcnt(1)
	v_mfma_f32_16x16x32_bf16 v[10:13], v[134:137], v[228:231], v[10:13]
	v_mfma_f32_16x16x32_bf16 v[2:5], v[142:145], v[228:231], v[2:5]
	v_mfma_f32_16x16x32_bf16 v[58:61], v[138:141], v[198:201], v[58:61]
	v_mfma_f32_16x16x32_bf16 v[50:53], v[146:149], v[198:201], v[50:53]
	v_mfma_f32_16x16x32_bf16 v[42:45], v[138:141], v[206:209], v[42:45]
	v_mfma_f32_16x16x32_bf16 v[34:37], v[146:149], v[206:209], v[34:37]
	v_mfma_f32_16x16x32_bf16 v[26:29], v[138:141], v[224:227], v[26:29]
	v_mfma_f32_16x16x32_bf16 v[18:21], v[146:149], v[224:227], v[18:21]
	s_waitcnt lgkmcnt(0)
	v_mfma_f32_16x16x32_bf16 v[10:13], v[138:141], v[232:235], v[10:13]
	v_mfma_f32_16x16x32_bf16 v[2:5], v[146:149], v[232:235], v[2:5]
	s_setprio 0
	s_setprio 1
	v_mfma_f32_16x16x32_bf16 v[62:65], v[150:153], v[184:187], v[62:65]
	v_mfma_f32_16x16x32_bf16 v[54:57], v[158:161], v[184:187], v[54:57]
	v_mfma_f32_16x16x32_bf16 v[46:49], v[150:153], v[202:205], v[46:49]
	v_mfma_f32_16x16x32_bf16 v[38:41], v[158:161], v[202:205], v[38:41]
	v_mfma_f32_16x16x32_bf16 v[30:33], v[150:153], v[210:213], v[30:33]
	v_mfma_f32_16x16x32_bf16 v[22:25], v[158:161], v[210:213], v[22:25]
	v_mfma_f32_16x16x32_bf16 v[14:17], v[150:153], v[228:231], v[14:17]
	v_mfma_f32_16x16x32_bf16 v[6:9], v[158:161], v[228:231], v[6:9]
	v_mfma_f32_16x16x32_bf16 v[62:65], v[154:157], v[198:201], v[62:65]
	v_mfma_f32_16x16x32_bf16 v[54:57], v[180:183], v[198:201], v[54:57]
	v_mfma_f32_16x16x32_bf16 v[46:49], v[154:157], v[206:209], v[46:49]
	v_mfma_f32_16x16x32_bf16 v[38:41], v[180:183], v[206:209], v[38:41]
	v_mfma_f32_16x16x32_bf16 v[30:33], v[154:157], v[224:227], v[30:33]
	v_mfma_f32_16x16x32_bf16 v[22:25], v[180:183], v[224:227], v[22:25]
	v_mfma_f32_16x16x32_bf16 v[14:17], v[154:157], v[232:235], v[14:17]
	v_mfma_f32_16x16x32_bf16 v[6:9], v[180:183], v[232:235], v[6:9]
	s_setprio 0
	s_barrier
	s_add_i32 s1, s1, 2
	s_add_u32 s60, s60, 0x100
	s_addc_u32 s61, s61, 0
	s_add_u32 s84, s84, 0x100
	s_addc_u32 s85, s85, 0
	s_cmp_gt_u32 s1, 13
	s_cbranch_scc1 .LBB0_1178

; #define PG8_STAGE(bufoff, gbase, voff) do { _Pragma("unroll") for (int _i = 0; _i < 2; ++_i) \
;         glds16_asm((const char*)(gbase) + (voff)[_i], ldsb + (unsigned)((bufoff) + _i * 8192)); } while (0)
; #define PG8_LDA(dst, b, h) do { _Pragma("unroll") for (int m = 0; m < 4; ++m) _Pragma("unroll") for (int k = 0; k < 2; ++k) dst[m][k] = *(const PG8_LAS bf16x8*)(lds + PG8_SA(b, h) + aoff + m * 2048 + k * 1024); } while (0)
; #define PG8_LDB(dst, b, h) do { _Pragma("unroll") for (int n = 0; n < 2; ++n) _Pragma("unroll") for (int k = 0; k < 2; ++k) dst[n][k] = *(const PG8_LAS bf16x8*)(lds + PG8_SB(b, h) + boff + n * 2048 + k * 1024); } while (0)
; #define PG8_MMA(ai, bj, At, Bt) do { __builtin_amdgcn_s_setprio(1); _Pragma("unroll") for (int m = 0; m < 4; ++m) _Pragma("unroll") for (int n = 0; n < 2; ++n) _Pragma("unroll") for (int k = 0; k < 2; ++k) \
;         acc[ai][bj][m][n] = __builtin_amdgcn_mfma_f32_16x16x32_bf16(Bt[n][k], At[m][k], acc[ai][bj][m][n], 0, 0, 0); __builtin_amdgcn_s_setprio(0); } while (0)
; #define PG8_WAIT_V(n) asm volatile("s_waitcnt vmcnt(" #n ")" ::: "memory")
; #define PG8_WAIT_L(n) asm volatile("s_waitcnt lgkmcnt(" #n ")" ::: "memory")
; #define PG8_BAR __builtin_amdgcn_s_barrier()
; #define PG8_SCHED __builtin_amdgcn_sched_barrier(0)
; template <class Epi, class Sched, bool ALIGN_EPI = false, bool SP2 = false>
; __device__ __forceinline__ void gemm_phase(PG8_LAS unsigned char* lds, const Gemm g, const Sched& S, const Epi& E, int wave_u) {
;     ...
;             PG8_LDB(B0, 0, 0); PG8_LDB(B1, 0, 1); PG8_SCHED; PG8_LDA(At, 0, 0); PG8_STAGE(PG8_SA(1, 1), a1 + hstep, voffA);
;             PG8_WAIT_V(8); PG8_WAIT_L(0); PG8_BAR; PG8_MMA(0, 0, At, B0); PG8_MMA(0, 1, At, B1); PG8_BAR; PG8_SCHED;
;             PG8_LDA(At, 0, 1); PG8_STAGE(PG8_SB(0, 0), b2, voffB); PG8_STAGE(PG8_SB(0, 1), b2 + hstep, voffB); PG8_STAGE(PG8_SA(0, 0), a2, voffA);
;             PG8_WAIT_V(8); PG8_WAIT_L(0); PG8_BAR; PG8_MMA(1, 0, At, B0); PG8_MMA(1, 1, At, B1); PG8_BAR; PG8_SCHED;
.LBB0_1428:
	v_add_u32_e32 v0, 0x10000, v227
	ds_read_b128 v[62:65], v0
	ds_read_b128 v[74:77], v0 offset:1024
	ds_read_b128 v[90:93], v0 offset:2048
	ds_read_b128 v[98:101], v0 offset:3072
	v_add_u32_e32 v0, 0x14000, v227
	s_add_u32 s46, s28, 0xfff50080
	ds_read_b128 v[114:117], v0
	ds_read_b128 v[122:125], v0 offset:1024
	ds_read_b128 v[138:141], v0 offset:2048
	ds_read_b128 v[146:149], v0 offset:3072
	s_addc_u32 s47, s29, -1
	s_and_b64 s[44:45], s[44:45], exec
	s_cselect_b32 s56, s22, s46
	s_cselect_b32 s57, s23, s47
	s_cselect_b32 s45, s25, s61
	s_cselect_b32 s44, s24, s60
	s_add_u32 s46, s56, 0x80
	s_addc_u32 s47, s57, 0
	s_add_u32 s48, s44, 0x80
	s_addc_u32 s49, s45, 0
	ds_read_b128 v[158:161], v228
	ds_read_b128 v[162:165], v228 offset:1024
	ds_read_b128 v[174:177], v228 offset:2048
	ds_read_b128 v[178:181], v228 offset:3072
	ds_read_b128 v[182:185], v228 offset:4096
	ds_read_b128 v[186:189], v228 offset:5120
	ds_read_b128 v[210:213], v228 offset:6144
	ds_read_b128 v[230:233], v228 offset:7168
	s_mov_b32 m0, s7
	s_nop 0
	global_load_lds_dwordx4 v198, s[28:29]
	s_mov_b32 m0, s75
	s_nop 0
	global_load_lds_dwordx4 v202, s[28:29]
	s_waitcnt vmcnt(8)
	s_waitcnt lgkmcnt(0)
	s_barrier
	s_setprio 1
	s_waitcnt lgkmcnt(7)
	v_mfma_f32_16x16x32_bf16 v[170:173], v[62:65], v[158:161], v[170:173]
	v_mfma_f32_16x16x32_bf16 v[166:169], v[90:93], v[158:161], v[166:169]
	s_waitcnt lgkmcnt(5)
	v_mfma_f32_16x16x32_bf16 v[142:145], v[62:65], v[174:177], v[142:145]
	v_mfma_f32_16x16x32_bf16 v[134:137], v[90:93], v[174:177], v[134:137]
	s_waitcnt lgkmcnt(3)
	v_mfma_f32_16x16x32_bf16 v[118:121], v[62:65], v[182:185], v[118:121]
	v_mfma_f32_16x16x32_bf16 v[110:113], v[90:93], v[182:185], v[110:113]
	s_waitcnt lgkmcnt(1)
	v_mfma_f32_16x16x32_bf16 v[94:97], v[62:65], v[210:213], v[94:97]
	v_mfma_f32_16x16x32_bf16 v[86:89], v[90:93], v[210:213], v[86:89]
	v_mfma_f32_16x16x32_bf16 v[170:173], v[74:77], v[162:165], v[170:173]
	v_mfma_f32_16x16x32_bf16 v[166:169], v[98:101], v[162:165], v[166:169]
	v_mfma_f32_16x16x32_bf16 v[142:145], v[74:77], v[178:181], v[142:145]
	v_mfma_f32_16x16x32_bf16 v[134:137], v[98:101], v[178:181], v[134:137]
	v_mfma_f32_16x16x32_bf16 v[118:121], v[74:77], v[186:189], v[118:121]
	v_mfma_f32_16x16x32_bf16 v[110:113], v[98:101], v[186:189], v[110:113]
	s_waitcnt lgkmcnt(0)
	v_mfma_f32_16x16x32_bf16 v[94:97], v[74:77], v[230:233], v[94:97]
	v_mfma_f32_16x16x32_bf16 v[86:89], v[98:101], v[230:233], v[86:89]
	s_setprio 0
	s_setprio 1
	v_mfma_f32_16x16x32_bf16 v[154:157], v[114:117], v[158:161], v[154:157]
	v_mfma_f32_16x16x32_bf16 v[150:153], v[138:141], v[158:161], v[150:153]
	v_mfma_f32_16x16x32_bf16 v[130:133], v[114:117], v[174:177], v[130:133]
	v_mfma_f32_16x16x32_bf16 v[126:129], v[138:141], v[174:177], v[126:129]
	v_mfma_f32_16x16x32_bf16 v[106:109], v[114:117], v[182:185], v[106:109]
	v_mfma_f32_16x16x32_bf16 v[102:105], v[138:141], v[182:185], v[102:105]
	v_mfma_f32_16x16x32_bf16 v[82:85], v[114:117], v[210:213], v[82:85]
	v_mfma_f32_16x16x32_bf16 v[78:81], v[138:141], v[210:213], v[78:81]
	v_mfma_f32_16x16x32_bf16 v[154:157], v[122:125], v[162:165], v[154:157]
	v_mfma_f32_16x16x32_bf16 v[150:153], v[146:149], v[162:165], v[150:153]
	v_mfma_f32_16x16x32_bf16 v[130:133], v[122:125], v[178:181], v[130:133]
	v_mfma_f32_16x16x32_bf16 v[126:129], v[146:149], v[178:181], v[126:129]
	v_mfma_f32_16x16x32_bf16 v[106:109], v[122:125], v[186:189], v[106:109]
	v_mfma_f32_16x16x32_bf16 v[102:105], v[146:149], v[186:189], v[102:105]
	v_mfma_f32_16x16x32_bf16 v[82:85], v[122:125], v[230:233], v[82:85]
	v_mfma_f32_16x16x32_bf16 v[78:81], v[146:149], v[230:233], v[78:81]
	s_setprio 0
	s_barrier
	ds_read_b128 v[158:161], v228 offset:16384
	ds_read_b128 v[162:165], v228 offset:17408
	ds_read_b128 v[174:177], v228 offset:18432
	ds_read_b128 v[178:181], v228 offset:19456
	ds_read_b128 v[182:185], v228 offset:20480
	ds_read_b128 v[186:189], v228 offset:21504
	ds_read_b128 v[210:213], v228 offset:22528
	ds_read_b128 v[230:233], v228 offset:23552
	s_mov_b32 m0, s27
	s_nop 0
	global_load_lds_dwordx4 v200, s[44:45]
	s_mov_b32 m0, s86
	s_nop 0
	global_load_lds_dwordx4 v204, s[44:45]
	s_add_u32 s64, s44, 0xb0000
	s_addc_u32 s65, s45, 0
	s_mov_b32 m0, s87
	s_nop 0
	global_load_lds_dwordx4 v200, s[64:65]
	s_mov_b32 m0, s88
	s_nop 0
	global_load_lds_dwordx4 v204, s[64:65]
	s_mov_b32 m0, s84
	s_nop 0
	global_load_lds_dwordx4 v198, s[56:57]
	s_mov_b32 m0, s89
	s_nop 0
	global_load_lds_dwordx4 v202, s[56:57]
	s_waitcnt vmcnt(8)
	s_waitcnt lgkmcnt(0)
	s_barrier
; #define PG8_STAGE(bufoff, gbase, voff) do { _Pragma("unroll") for (int _i = 0; _i < 2; ++_i) \
;         glds16_asm((const char*)(gbase) + (voff)[_i], ldsb + (unsigned)((bufoff) + _i * 8192)); } while (0)
; #define PG8_LDA(dst, b, h) do { _Pragma("unroll") for (int m = 0; m < 4; ++m) _Pragma("unroll") for (int k = 0; k < 2; ++k) dst[m][k] = *(const PG8_LAS bf16x8*)(lds + PG8_SA(b, h) + aoff + m * 2048 + k * 1024); } while (0)
; #define PG8_LDB(dst, b, h) do { _Pragma("unroll") for (int n = 0; n < 2; ++n) _Pragma("unroll") for (int k = 0; k < 2; ++k) dst[n][k] = *(const PG8_LAS bf16x8*)(lds + PG8_SB(b, h) + boff + n * 2048 + k * 1024); } while (0)
; #define PG8_MMA(ai, bj, At, Bt) do { __builtin_amdgcn_s_setprio(1); _Pragma("unroll") for (int m = 0; m < 4; ++m) _Pragma("unroll") for (int n = 0; n < 2; ++n) _Pragma("unroll") for (int k = 0; k < 2; ++k) \
;         acc[ai][bj][m][n] = __builtin_amdgcn_mfma_f32_16x16x32_bf16(Bt[n][k], At[m][k], acc[ai][bj][m][n], 0, 0, 0); __builtin_amdgcn_s_setprio(0); } while (0)
; #define PG8_WAIT_V(n) asm volatile("s_waitcnt vmcnt(" #n ")" ::: "memory")
; #define PG8_WAIT_L(n) asm volatile("s_waitcnt lgkmcnt(" #n ")" ::: "memory")
; #define PG8_BAR __builtin_amdgcn_s_barrier()
; #define PG8_SCHED __builtin_amdgcn_sched_barrier(0)
; template <class Epi, class Sched, bool ALIGN_EPI = false, bool SP2 = false>
; __device__ __forceinline__ void gemm_phase(PG8_LAS unsigned char* lds, const Gemm g, const Sched& S, const Epi& E, int wave_u) {
;     ...
;             PG8_WAIT_V(8); PG8_WAIT_L(0); PG8_BAR; PG8_MMA(1, 0, At, B0); PG8_MMA(1, 1, At, B1); PG8_BAR; PG8_SCHED;
;             PG8_LDB(B0, 1, 0); PG8_LDB(B1, 1, 1); PG8_SCHED; PG8_LDA(At, 1, 0); PG8_STAGE(PG8_SA(0, 1), a2 + hstep, voffA);
;             PG8_WAIT_V(8); PG8_WAIT_L(0); PG8_BAR; PG8_MMA(0, 0, At, B0); PG8_MMA(0, 1, At, B1); PG8_BAR; PG8_SCHED;
	s_setprio 1
	s_waitcnt lgkmcnt(7)
	v_mfma_f32_16x16x32_bf16 v[70:73], v[62:65], v[158:161], v[70:73]
	v_mfma_f32_16x16x32_bf16 v[66:69], v[90:93], v[158:161], v[66:69]
	s_waitcnt lgkmcnt(5)
	v_mfma_f32_16x16x32_bf16 v[46:49], v[62:65], v[174:177], v[46:49]
	v_mfma_f32_16x16x32_bf16 v[42:45], v[90:93], v[174:177], v[42:45]
	s_waitcnt lgkmcnt(3)
	v_mfma_f32_16x16x32_bf16 v[30:33], v[62:65], v[182:185], v[30:33]
	v_mfma_f32_16x16x32_bf16 v[26:29], v[90:93], v[182:185], v[26:29]
	s_waitcnt lgkmcnt(1)
	v_mfma_f32_16x16x32_bf16 v[14:17], v[62:65], v[210:213], v[14:17]
	v_mfma_f32_16x16x32_bf16 v[10:13], v[90:93], v[210:213], v[10:13]
	v_mfma_f32_16x16x32_bf16 v[70:73], v[74:77], v[162:165], v[70:73]
	v_mfma_f32_16x16x32_bf16 v[66:69], v[98:101], v[162:165], v[66:69]
	v_mfma_f32_16x16x32_bf16 v[46:49], v[74:77], v[178:181], v[46:49]
	v_mfma_f32_16x16x32_bf16 v[42:45], v[98:101], v[178:181], v[42:45]
	v_mfma_f32_16x16x32_bf16 v[30:33], v[74:77], v[186:189], v[30:33]
	v_mfma_f32_16x16x32_bf16 v[26:29], v[98:101], v[186:189], v[26:29]
	s_waitcnt lgkmcnt(0)
	v_mfma_f32_16x16x32_bf16 v[14:17], v[74:77], v[230:233], v[14:17]
	v_mfma_f32_16x16x32_bf16 v[10:13], v[98:101], v[230:233], v[10:13]
	s_setprio 0
	s_setprio 1
	v_mfma_f32_16x16x32_bf16 v[58:61], v[114:117], v[158:161], v[58:61]
	v_mfma_f32_16x16x32_bf16 v[54:57], v[138:141], v[158:161], v[54:57]
	v_mfma_f32_16x16x32_bf16 v[38:41], v[114:117], v[174:177], v[38:41]
	v_mfma_f32_16x16x32_bf16 v[34:37], v[138:141], v[174:177], v[34:37]
	v_mfma_f32_16x16x32_bf16 v[22:25], v[114:117], v[182:185], v[22:25]
	v_mfma_f32_16x16x32_bf16 v[18:21], v[138:141], v[182:185], v[18:21]
	v_mfma_f32_16x16x32_bf16 v[6:9], v[114:117], v[210:213], v[6:9]
	v_mfma_f32_16x16x32_bf16 v[2:5], v[138:141], v[210:213], v[2:5]
	v_mfma_f32_16x16x32_bf16 v[58:61], v[122:125], v[162:165], v[58:61]
	v_mfma_f32_16x16x32_bf16 v[54:57], v[146:149], v[162:165], v[54:57]
	v_mfma_f32_16x16x32_bf16 v[38:41], v[122:125], v[178:181], v[38:41]
	v_mfma_f32_16x16x32_bf16 v[34:37], v[146:149], v[178:181], v[34:37]
	v_mfma_f32_16x16x32_bf16 v[22:25], v[122:125], v[186:189], v[22:25]
	v_mfma_f32_16x16x32_bf16 v[18:21], v[146:149], v[186:189], v[18:21]
	v_mfma_f32_16x16x32_bf16 v[6:9], v[122:125], v[230:233], v[6:9]
	v_mfma_f32_16x16x32_bf16 v[2:5], v[146:149], v[230:233], v[2:5]
	s_setprio 0
	s_barrier
	v_add_u32_e32 v0, 0x18000, v227
	ds_read_b128 v[62:65], v0
	ds_read_b128 v[74:77], v0 offset:1024
	ds_read_b128 v[90:93], v0 offset:2048
	ds_read_b128 v[98:101], v0 offset:3072
	v_add_u32_e32 v0, 0x1c000, v227
	ds_read_b128 v[114:117], v0
	ds_read_b128 v[122:125], v0 offset:1024
	ds_read_b128 v[138:141], v0 offset:2048
	ds_read_b128 v[146:149], v0 offset:3072
	ds_read_b128 v[158:161], v228 offset:32768
	ds_read_b128 v[162:165], v228 offset:33792
	ds_read_b128 v[174:177], v228 offset:34816
	ds_read_b128 v[178:181], v228 offset:35840
	ds_read_b128 v[182:185], v228 offset:36864
	ds_read_b128 v[186:189], v228 offset:37888
	ds_read_b128 v[210:213], v228 offset:38912
	ds_read_b128 v[230:233], v228 offset:39936
	s_add_u32 s56, s56, 0xb0000
	s_addc_u32 s57, s57, 0
	s_mov_b32 m0, s90
	s_nop 0
	global_load_lds_dwordx4 v198, s[56:57]
	s_mov_b32 m0, s91
	s_nop 0
	global_load_lds_dwordx4 v202, s[56:57]
	s_waitcnt vmcnt(8)
	s_waitcnt lgkmcnt(0)
	s_barrier
	s_setprio 1
	s_waitcnt lgkmcnt(7)
	v_mfma_f32_16x16x32_bf16 v[170:173], v[62:65], v[158:161], v[170:173]
	v_mfma_f32_16x16x32_bf16 v[166:169], v[90:93], v[158:161], v[166:169]
	s_waitcnt lgkmcnt(5)
	v_mfma_f32_16x16x32_bf16 v[142:145], v[62:65], v[174:177], v[142:145]
	v_mfma_f32_16x16x32_bf16 v[134:137], v[90:93], v[174:177], v[134:137]
	s_waitcnt lgkmcnt(3)
	v_mfma_f32_16x16x32_bf16 v[118:121], v[62:65], v[182:185], v[118:121]
	v_mfma_f32_16x16x32_bf16 v[110:113], v[90:93], v[182:185], v[110:113]
	s_waitcnt lgkmcnt(1)
	v_mfma_f32_16x16x32_bf16 v[94:97], v[62:65], v[210:213], v[94:97]
	v_mfma_f32_16x16x32_bf16 v[86:89], v[90:93], v[210:213], v[86:89]
	v_mfma_f32_16x16x32_bf16 v[170:173], v[74:77], v[162:165], v[170:173]
	v_mfma_f32_16x16x32_bf16 v[166:169], v[98:101], v[162:165], v[166:169]
	v_mfma_f32_16x16x32_bf16 v[142:145], v[74:77], v[178:181], v[142:145]
	v_mfma_f32_16x16x32_bf16 v[134:137], v[98:101], v[178:181], v[134:137]
	v_mfma_f32_16x16x32_bf16 v[118:121], v[74:77], v[186:189], v[118:121]
	v_mfma_f32_16x16x32_bf16 v[110:113], v[98:101], v[186:189], v[110:113]
	s_waitcnt lgkmcnt(0)
	v_mfma_f32_16x16x32_bf16 v[94:97], v[74:77], v[230:233], v[94:97]
	v_mfma_f32_16x16x32_bf16 v[86:89], v[98:101], v[230:233], v[86:89]
	s_setprio 0
	s_setprio 1
	v_mfma_f32_16x16x32_bf16 v[154:157], v[114:117], v[158:161], v[154:157]
	v_mfma_f32_16x16x32_bf16 v[150:153], v[138:141], v[158:161], v[150:153]
	v_mfma_f32_16x16x32_bf16 v[130:133], v[114:117], v[174:177], v[130:133]
	v_mfma_f32_16x16x32_bf16 v[126:129], v[138:141], v[174:177], v[126:129]
	v_mfma_f32_16x16x32_bf16 v[106:109], v[114:117], v[182:185], v[106:109]
	v_mfma_f32_16x16x32_bf16 v[102:105], v[138:141], v[182:185], v[102:105]
	v_mfma_f32_16x16x32_bf16 v[82:85], v[114:117], v[210:213], v[82:85]
	v_mfma_f32_16x16x32_bf16 v[78:81], v[138:141], v[210:213], v[78:81]
	v_mfma_f32_16x16x32_bf16 v[154:157], v[122:125], v[162:165], v[154:157]
	v_mfma_f32_16x16x32_bf16 v[150:153], v[146:149], v[162:165], v[150:153]
	v_mfma_f32_16x16x32_bf16 v[130:133], v[122:125], v[178:181], v[130:133]
	v_mfma_f32_16x16x32_bf16 v[126:129], v[146:149], v[178:181], v[126:129]
	v_mfma_f32_16x16x32_bf16 v[106:109], v[122:125], v[186:189], v[106:109]
	v_mfma_f32_16x16x32_bf16 v[102:105], v[146:149], v[186:189], v[102:105]
	v_mfma_f32_16x16x32_bf16 v[82:85], v[122:125], v[230:233], v[82:85]
	v_mfma_f32_16x16x32_bf16 v[78:81], v[146:149], v[230:233], v[78:81]
	s_setprio 0
	s_barrier
; #define PG8_STAGE(bufoff, gbase, voff) do { _Pragma("unroll") for (int _i = 0; _i < 2; ++_i) \
;         glds16_asm((const char*)(gbase) + (voff)[_i], ldsb + (unsigned)((bufoff) + _i * 8192)); } while (0)
; #define PG8_LDA(dst, b, h) do { _Pragma("unroll") for (int m = 0; m < 4; ++m) _Pragma("unroll") for (int k = 0; k < 2; ++k) dst[m][k] = *(const PG8_LAS bf16x8*)(lds + PG8_SA(b, h) + aoff + m * 2048 + k * 1024); } while (0)
; #define PG8_MMA(ai, bj, At, Bt) do { __builtin_amdgcn_s_setprio(1); _Pragma("unroll") for (int m = 0; m < 4; ++m) _Pragma("unroll") for (int n = 0; n < 2; ++n) _Pragma("unroll") for (int k = 0; k < 2; ++k) \
;         acc[ai][bj][m][n] = __builtin_amdgcn_mfma_f32_16x16x32_bf16(Bt[n][k], At[m][k], acc[ai][bj][m][n], 0, 0, 0); __builtin_amdgcn_s_setprio(0); } while (0)
; #define PG8_WAIT_V(n) asm volatile("s_waitcnt vmcnt(" #n ")" ::: "memory")
; #define PG8_WAIT_L(n) asm volatile("s_waitcnt lgkmcnt(" #n ")" ::: "memory")
; #define PG8_BAR __builtin_amdgcn_s_barrier()
; #define PG8_SCHED __builtin_amdgcn_sched_barrier(0)
; template <class Epi, class Sched, bool ALIGN_EPI = false, bool SP2 = false>
; __device__ __forceinline__ void gemm_phase(PG8_LAS unsigned char* lds, const Gemm g, const Sched& S, const Epi& E, int wave_u) {
;     ...
;         for (int t = 0; t < nt; t += 2) {
;     ...
;             PG8_LDA(At, 1, 1); PG8_STAGE(PG8_SB(1, 0), b3, voffB); PG8_STAGE(PG8_SB(1, 1), b3 + hstep, voffB); PG8_STAGE(PG8_SA(1, 0), a3, voffA);
;             PG8_WAIT_V(8); PG8_WAIT_L(0); PG8_BAR; PG8_MMA(1, 0, At, B0); PG8_MMA(1, 1, At, B1); PG8_BAR; PG8_SCHED;
	ds_read_b128 v[158:161], v228 offset:49152
	ds_read_b128 v[162:165], v228 offset:50176
	ds_read_b128 v[174:177], v228 offset:51200
	ds_read_b128 v[178:181], v228 offset:52224
	ds_read_b128 v[182:185], v228 offset:53248
	ds_read_b128 v[186:189], v228 offset:54272
	ds_read_b128 v[210:213], v228 offset:55296
	ds_read_b128 v[230:233], v228 offset:56320
	s_mov_b32 m0, s62
	s_nop 0
	global_load_lds_dwordx4 v200, s[48:49]
	s_add_u32 s44, s44, 0xb0080
	s_mov_b32 m0, s63
	s_nop 0
	global_load_lds_dwordx4 v204, s[48:49]
	s_addc_u32 s45, s45, 0
	s_mov_b32 m0, s66
	s_nop 0
	global_load_lds_dwordx4 v200, s[44:45]
	s_mov_b32 m0, s67
	s_nop 0
	global_load_lds_dwordx4 v204, s[44:45]
	s_mov_b32 m0, s40
	s_nop 0
	global_load_lds_dwordx4 v198, s[46:47]
	s_mov_b32 m0, s41
	s_nop 0
	global_load_lds_dwordx4 v202, s[46:47]
	s_waitcnt vmcnt(8)
	s_waitcnt lgkmcnt(0)
	s_barrier
	s_setprio 1
	s_waitcnt lgkmcnt(7)
	v_mfma_f32_16x16x32_bf16 v[70:73], v[62:65], v[158:161], v[70:73]
	v_mfma_f32_16x16x32_bf16 v[66:69], v[90:93], v[158:161], v[66:69]
	s_waitcnt lgkmcnt(5)
	v_mfma_f32_16x16x32_bf16 v[46:49], v[62:65], v[174:177], v[46:49]
	v_mfma_f32_16x16x32_bf16 v[42:45], v[90:93], v[174:177], v[42:45]
	s_waitcnt lgkmcnt(3)
	v_mfma_f32_16x16x32_bf16 v[30:33], v[62:65], v[182:185], v[30:33]
	v_mfma_f32_16x16x32_bf16 v[26:29], v[90:93], v[182:185], v[26:29]
	s_waitcnt lgkmcnt(1)
	v_mfma_f32_16x16x32_bf16 v[14:17], v[62:65], v[210:213], v[14:17]
	v_mfma_f32_16x16x32_bf16 v[10:13], v[90:93], v[210:213], v[10:13]
	v_mfma_f32_16x16x32_bf16 v[70:73], v[74:77], v[162:165], v[70:73]
	v_mfma_f32_16x16x32_bf16 v[66:69], v[98:101], v[162:165], v[66:69]
	v_mfma_f32_16x16x32_bf16 v[46:49], v[74:77], v[178:181], v[46:49]
	v_mfma_f32_16x16x32_bf16 v[42:45], v[98:101], v[178:181], v[42:45]
	v_mfma_f32_16x16x32_bf16 v[30:33], v[74:77], v[186:189], v[30:33]
	v_mfma_f32_16x16x32_bf16 v[26:29], v[98:101], v[186:189], v[26:29]
	s_waitcnt lgkmcnt(0)
	v_mfma_f32_16x16x32_bf16 v[14:17], v[74:77], v[230:233], v[14:17]
	v_mfma_f32_16x16x32_bf16 v[10:13], v[98:101], v[230:233], v[10:13]
	s_setprio 0
	s_setprio 1
	v_mfma_f32_16x16x32_bf16 v[58:61], v[114:117], v[158:161], v[58:61]
	v_mfma_f32_16x16x32_bf16 v[54:57], v[138:141], v[158:161], v[54:57]
	v_mfma_f32_16x16x32_bf16 v[38:41], v[114:117], v[174:177], v[38:41]
	v_mfma_f32_16x16x32_bf16 v[34:37], v[138:141], v[174:177], v[34:37]
	v_mfma_f32_16x16x32_bf16 v[22:25], v[114:117], v[182:185], v[22:25]
	v_mfma_f32_16x16x32_bf16 v[18:21], v[138:141], v[182:185], v[18:21]
	v_mfma_f32_16x16x32_bf16 v[6:9], v[114:117], v[210:213], v[6:9]
	v_mfma_f32_16x16x32_bf16 v[2:5], v[138:141], v[210:213], v[2:5]
	v_mfma_f32_16x16x32_bf16 v[58:61], v[122:125], v[162:165], v[58:61]
	v_mfma_f32_16x16x32_bf16 v[54:57], v[146:149], v[162:165], v[54:57]
	v_mfma_f32_16x16x32_bf16 v[38:41], v[122:125], v[178:181], v[38:41]
	v_mfma_f32_16x16x32_bf16 v[34:37], v[146:149], v[178:181], v[34:37]
	v_mfma_f32_16x16x32_bf16 v[22:25], v[122:125], v[186:189], v[22:25]
	v_mfma_f32_16x16x32_bf16 v[18:21], v[146:149], v[186:189], v[18:21]
	v_mfma_f32_16x16x32_bf16 v[6:9], v[122:125], v[230:233], v[6:9]
	v_mfma_f32_16x16x32_bf16 v[2:5], v[146:149], v[230:233], v[2:5]
	s_setprio 0
	s_barrier
	s_add_i32 s1, s1, 2
	s_add_u32 s28, s28, 0x100
	s_addc_u32 s29, s29, 0
	s_add_u32 s60, s60, 0x100
	s_addc_u32 s61, s61, 0
	s_cmp_gt_u32 s1, 41
	s_cbranch_scc1 .LBB0_1431
